# scanner operand reads as ds_read_b64 pairs (better LDS throughput than b128 here), wait-then-burst ordering
# speedup vs baseline: 1.0046x; 1.0046x over previous
.Lstag_done:
	s_and_b32 s1, s0, 1
	s_lshl_b32 s31, s1, 8
	s_mul_i32 s30, s1, 0xa000
	s_add_i32 s31, s31, 0x18000
	v_add_u32_e32 v6, s30, v151
	v_mov_b32_e32 v8, s31
	v_lshl_add_u32 v7, s1, 13, v0
	v_lshl_add_u32 v9, s1, 11, v39
	v_add_u32_e32 v22, 0x400, v9
	ds_read_b64 v[58:59], v6
	ds_read_b64 v[60:61], v6 offset:8
	ds_read_b64 v[62:63], v6 offset:16
	ds_read_b64 v[64:65], v6 offset:24
	ds_read_b64 v[66:67], v6 offset:32
	ds_read_b64 v[68:69], v6 offset:40
	ds_read_b64 v[70:71], v6 offset:48
	ds_read_b64 v[72:73], v6 offset:56
	ds_read_b64 v[74:75], v6 offset:64
	ds_read_b64 v[76:77], v6 offset:72
	ds_read2st64_b32 v[118:119], v7 offset1:1
	ds_read_b128 v[120:123], v8
	ds_read_b64 v[78:79], v6 offset:1280
	ds_read_b64 v[80:81], v6 offset:1288
	ds_read_b64 v[82:83], v6 offset:1296
	ds_read_b64 v[84:85], v6 offset:1304
	ds_read_b64 v[86:87], v6 offset:1312
	ds_read_b64 v[88:89], v6 offset:1320
	ds_read_b64 v[90:91], v6 offset:1328
	ds_read_b64 v[92:93], v6 offset:1336
	ds_read_b64 v[94:95], v6 offset:1344
	ds_read_b64 v[96:97], v6 offset:1352
	s_waitcnt lgkmcnt(10)
	ds_read_b64 v[98:99], v6 offset:2560
	ds_read_b64 v[100:101], v6 offset:2568
	ds_read_b64 v[102:103], v6 offset:2576
	ds_read_b64 v[104:105], v6 offset:2584
	ds_read_b64 v[106:107], v6 offset:2592
	ds_read_b64 v[108:109], v6 offset:2600
	ds_read_b64 v[110:111], v6 offset:2608
	ds_read_b64 v[112:113], v6 offset:2616
	ds_read_b64 v[114:115], v6 offset:2624
	ds_read_b64 v[116:117], v6 offset:2632
	ds_read2st64_b32 v[206:207], v7 offset0:2 offset1:3
	ds_read_b128 v[208:211], v8 offset:16
	v_pk_mul_f32 v[10:11], v[2:3], v[58:59] op_sel_hi:[0,1]
	v_pk_fma_f32 v[10:11], v[2:3], v[60:61], v[10:11] op_sel:[1,0,0] op_sel_hi:[1,1,1]
	v_pk_fma_f32 v[10:11], v[4:5], v[62:63], v[10:11] op_sel_hi:[0,1,1]
	v_pk_fma_f32 v[10:11], v[4:5], v[64:65], v[10:11] op_sel:[1,0,0] op_sel_hi:[1,1,1]
	v_pk_mul_f32 v[18:19], v[74:75], v[118:119] op_sel_hi:[1,0]
	v_pk_mul_f32 v[20:21], v[76:77], v[118:119] op_sel_hi:[1,0]
	v_add_f32_dpp v10, v10, v10 quad_perm:[1,0,3,2] row_mask:0xf bank_mask:0xf bound_ctrl:1
	v_add_f32_dpp v11, v11, v11 quad_perm:[1,0,3,2] row_mask:0xf bank_mask:0xf bound_ctrl:1
	v_pk_fma_f32 v[18:19], v[2:3], v[66:67], v[18:19]
	v_add_f32_dpp v10, v10, v10 quad_perm:[2,3,0,1] row_mask:0xf bank_mask:0xf bound_ctrl:1
	v_add_f32_dpp v11, v11, v11 quad_perm:[2,3,0,1] row_mask:0xf bank_mask:0xf bound_ctrl:1
	v_pk_fma_f32 v[20:21], v[4:5], v[68:69], v[20:21]
	v_add_f32_dpp v10, v10, v10 row_half_mirror row_mask:0xf bank_mask:0xf bound_ctrl:1
	v_add_f32_dpp v11, v11, v11 row_half_mirror row_mask:0xf bank_mask:0xf bound_ctrl:1
	s_nop 0
	v_add_f32_dpp v10, v10, v10 row_mirror row_mask:0xf bank_mask:0xf bound_ctrl:1
	v_add_f32_dpp v11, v11, v11 row_mirror row_mask:0xf bank_mask:0xf bound_ctrl:1
	v_pk_fma_f32 v[2:3], v[70:71], v[10:11], v[18:19] op_sel_hi:[1,0,1]
	v_pk_fma_f32 v[4:5], v[72:73], v[10:11], v[20:21] op_sel_hi:[1,0,1]
	v_fmac_f32_e32 v11, v120, v10
	v_fmac_f32_e32 v11, v118, v121
	s_waitcnt lgkmcnt(12)
	ds_read_b64 v[186:187], v6 offset:3840
	ds_read_b64 v[188:189], v6 offset:3848
	ds_read_b64 v[190:191], v6 offset:3856
	ds_read_b64 v[192:193], v6 offset:3864
	ds_read_b64 v[194:195], v6 offset:3872
	ds_read_b64 v[196:197], v6 offset:3880
	ds_read_b64 v[198:199], v6 offset:3888
	ds_read_b64 v[200:201], v6 offset:3896
	ds_read_b64 v[202:203], v6 offset:3904
	ds_read_b64 v[204:205], v6 offset:3912
	v_pk_mul_f32 v[12:13], v[2:3], v[78:79] op_sel_hi:[0,1]
	v_pk_fma_f32 v[12:13], v[2:3], v[80:81], v[12:13] op_sel:[1,0,0] op_sel_hi:[1,1,1]
	v_pk_fma_f32 v[12:13], v[4:5], v[82:83], v[12:13] op_sel_hi:[0,1,1]
	v_pk_fma_f32 v[12:13], v[4:5], v[84:85], v[12:13] op_sel:[1,0,0] op_sel_hi:[1,1,1]
	v_pk_mul_f32 v[18:19], v[94:95], v[118:119] op_sel:[0,1] op_sel_hi:[1,1]
	v_pk_mul_f32 v[20:21], v[96:97], v[118:119] op_sel:[0,1] op_sel_hi:[1,1]
	v_add_f32_dpp v12, v12, v12 quad_perm:[1,0,3,2] row_mask:0xf bank_mask:0xf bound_ctrl:1
	v_add_f32_dpp v13, v13, v13 quad_perm:[1,0,3,2] row_mask:0xf bank_mask:0xf bound_ctrl:1
	v_pk_fma_f32 v[18:19], v[2:3], v[86:87], v[18:19]
	v_add_f32_dpp v12, v12, v12 quad_perm:[2,3,0,1] row_mask:0xf bank_mask:0xf bound_ctrl:1
	v_add_f32_dpp v13, v13, v13 quad_perm:[2,3,0,1] row_mask:0xf bank_mask:0xf bound_ctrl:1
	v_pk_fma_f32 v[20:21], v[4:5], v[88:89], v[20:21]
	v_add_f32_dpp v12, v12, v12 row_half_mirror row_mask:0xf bank_mask:0xf bound_ctrl:1
	v_add_f32_dpp v13, v13, v13 row_half_mirror row_mask:0xf bank_mask:0xf bound_ctrl:1
	s_nop 0
	v_add_f32_dpp v12, v12, v12 row_mirror row_mask:0xf bank_mask:0xf bound_ctrl:1
	v_add_f32_dpp v13, v13, v13 row_mirror row_mask:0xf bank_mask:0xf bound_ctrl:1
	v_pk_fma_f32 v[2:3], v[90:91], v[12:13], v[18:19] op_sel_hi:[1,0,1]
	v_pk_fma_f32 v[4:5], v[92:93], v[12:13], v[20:21] op_sel_hi:[1,0,1]
	v_fmac_f32_e32 v13, v122, v12
	v_fmac_f32_e32 v13, v119, v123
	ds_write2_b32 v9, v11, v13 offset1:16
	s_waitcnt lgkmcnt(11)
	ds_read_b64 v[58:59], v6 offset:5120
	ds_read_b64 v[60:61], v6 offset:5128
	ds_read_b64 v[62:63], v6 offset:5136
	ds_read_b64 v[64:65], v6 offset:5144
	ds_read_b64 v[66:67], v6 offset:5152
	ds_read_b64 v[68:69], v6 offset:5160
	ds_read_b64 v[70:71], v6 offset:5168
	ds_read_b64 v[72:73], v6 offset:5176
	ds_read_b64 v[74:75], v6 offset:5184
	ds_read_b64 v[76:77], v6 offset:5192
	ds_read2st64_b32 v[118:119], v7 offset0:4 offset1:5
	ds_read_b128 v[120:123], v8 offset:32
	v_pk_mul_f32 v[14:15], v[2:3], v[98:99] op_sel_hi:[0,1]
	v_pk_fma_f32 v[14:15], v[2:3], v[100:101], v[14:15] op_sel:[1,0,0] op_sel_hi:[1,1,1]
	v_pk_fma_f32 v[14:15], v[4:5], v[102:103], v[14:15] op_sel_hi:[0,1,1]
	v_pk_fma_f32 v[14:15], v[4:5], v[104:105], v[14:15] op_sel:[1,0,0] op_sel_hi:[1,1,1]
	v_pk_mul_f32 v[18:19], v[114:115], v[206:207] op_sel_hi:[1,0]
	v_pk_mul_f32 v[20:21], v[116:117], v[206:207] op_sel_hi:[1,0]
	v_add_f32_dpp v14, v14, v14 quad_perm:[1,0,3,2] row_mask:0xf bank_mask:0xf bound_ctrl:1
	v_add_f32_dpp v15, v15, v15 quad_perm:[1,0,3,2] row_mask:0xf bank_mask:0xf bound_ctrl:1
	v_pk_fma_f32 v[18:19], v[2:3], v[106:107], v[18:19]
	v_add_f32_dpp v14, v14, v14 quad_perm:[2,3,0,1] row_mask:0xf bank_mask:0xf bound_ctrl:1
	v_add_f32_dpp v15, v15, v15 quad_perm:[2,3,0,1] row_mask:0xf bank_mask:0xf bound_ctrl:1
	v_pk_fma_f32 v[20:21], v[4:5], v[108:109], v[20:21]
	v_add_f32_dpp v14, v14, v14 row_half_mirror row_mask:0xf bank_mask:0xf bound_ctrl:1
	v_add_f32_dpp v15, v15, v15 row_half_mirror row_mask:0xf bank_mask:0xf bound_ctrl:1
	s_nop 0
	v_add_f32_dpp v14, v14, v14 row_mirror row_mask:0xf bank_mask:0xf bound_ctrl:1
	v_add_f32_dpp v15, v15, v15 row_mirror row_mask:0xf bank_mask:0xf bound_ctrl:1
	v_pk_fma_f32 v[2:3], v[110:111], v[14:15], v[18:19] op_sel_hi:[1,0,1]
	v_pk_fma_f32 v[4:5], v[112:113], v[14:15], v[20:21] op_sel_hi:[1,0,1]
	v_fmac_f32_e32 v15, v208, v14
	v_fmac_f32_e32 v15, v206, v209
	s_waitcnt lgkmcnt(13)
	ds_read_b64 v[78:79], v6 offset:6400
	ds_read_b64 v[80:81], v6 offset:6408
	ds_read_b64 v[82:83], v6 offset:6416
	ds_read_b64 v[84:85], v6 offset:6424
	ds_read_b64 v[86:87], v6 offset:6432
	ds_read_b64 v[88:89], v6 offset:6440
	ds_read_b64 v[90:91], v6 offset:6448
	ds_read_b64 v[92:93], v6 offset:6456
	ds_read_b64 v[94:95], v6 offset:6464
	ds_read_b64 v[96:97], v6 offset:6472
	v_pk_mul_f32 v[16:17], v[2:3], v[186:187] op_sel_hi:[0,1]
	v_pk_fma_f32 v[16:17], v[2:3], v[188:189], v[16:17] op_sel:[1,0,0] op_sel_hi:[1,1,1]
	v_pk_fma_f32 v[16:17], v[4:5], v[190:191], v[16:17] op_sel_hi:[0,1,1]
	v_pk_fma_f32 v[16:17], v[4:5], v[192:193], v[16:17] op_sel:[1,0,0] op_sel_hi:[1,1,1]
	v_pk_mul_f32 v[18:19], v[202:203], v[206:207] op_sel:[0,1] op_sel_hi:[1,1]
	v_pk_mul_f32 v[20:21], v[204:205], v[206:207] op_sel:[0,1] op_sel_hi:[1,1]
	v_add_f32_dpp v16, v16, v16 quad_perm:[1,0,3,2] row_mask:0xf bank_mask:0xf bound_ctrl:1
	v_add_f32_dpp v17, v17, v17 quad_perm:[1,0,3,2] row_mask:0xf bank_mask:0xf bound_ctrl:1
	v_pk_fma_f32 v[18:19], v[2:3], v[194:195], v[18:19]
	v_add_f32_dpp v16, v16, v16 quad_perm:[2,3,0,1] row_mask:0xf bank_mask:0xf bound_ctrl:1
	v_add_f32_dpp v17, v17, v17 quad_perm:[2,3,0,1] row_mask:0xf bank_mask:0xf bound_ctrl:1
	v_pk_fma_f32 v[20:21], v[4:5], v[196:197], v[20:21]
	v_add_f32_dpp v16, v16, v16 row_half_mirror row_mask:0xf bank_mask:0xf bound_ctrl:1
	v_add_f32_dpp v17, v17, v17 row_half_mirror row_mask:0xf bank_mask:0xf bound_ctrl:1
	s_nop 0
	v_add_f32_dpp v16, v16, v16 row_mirror row_mask:0xf bank_mask:0xf bound_ctrl:1
	v_add_f32_dpp v17, v17, v17 row_mirror row_mask:0xf bank_mask:0xf bound_ctrl:1
	v_pk_fma_f32 v[2:3], v[198:199], v[16:17], v[18:19] op_sel_hi:[1,0,1]
	v_pk_fma_f32 v[4:5], v[200:201], v[16:17], v[20:21] op_sel_hi:[1,0,1]
	v_fmac_f32_e32 v17, v210, v16
	v_fmac_f32_e32 v17, v207, v211
	ds_write2_b32 v9, v15, v17 offset0:32 offset1:48
	s_waitcnt lgkmcnt(11)
	ds_read_b64 v[98:99], v6 offset:7680
	ds_read_b64 v[100:101], v6 offset:7688
	ds_read_b64 v[102:103], v6 offset:7696
	ds_read_b64 v[104:105], v6 offset:7704
	ds_read_b64 v[106:107], v6 offset:7712
	ds_read_b64 v[108:109], v6 offset:7720
	ds_read_b64 v[110:111], v6 offset:7728
	ds_read_b64 v[112:113], v6 offset:7736
	ds_read_b64 v[114:115], v6 offset:7744
	ds_read_b64 v[116:117], v6 offset:7752
	ds_read2st64_b32 v[206:207], v7 offset0:6 offset1:7
	ds_read_b128 v[208:211], v8 offset:48
	v_pk_mul_f32 v[10:11], v[2:3], v[58:59] op_sel_hi:[0,1]
	v_pk_fma_f32 v[10:11], v[2:3], v[60:61], v[10:11] op_sel:[1,0,0] op_sel_hi:[1,1,1]
	v_pk_fma_f32 v[10:11], v[4:5], v[62:63], v[10:11] op_sel_hi:[0,1,1]
	v_pk_fma_f32 v[10:11], v[4:5], v[64:65], v[10:11] op_sel:[1,0,0] op_sel_hi:[1,1,1]
	v_pk_mul_f32 v[18:19], v[74:75], v[118:119] op_sel_hi:[1,0]
	v_pk_mul_f32 v[20:21], v[76:77], v[118:119] op_sel_hi:[1,0]
	v_add_f32_dpp v10, v10, v10 quad_perm:[1,0,3,2] row_mask:0xf bank_mask:0xf bound_ctrl:1
	v_add_f32_dpp v11, v11, v11 quad_perm:[1,0,3,2] row_mask:0xf bank_mask:0xf bound_ctrl:1
	v_pk_fma_f32 v[18:19], v[2:3], v[66:67], v[18:19]
	v_add_f32_dpp v10, v10, v10 quad_perm:[2,3,0,1] row_mask:0xf bank_mask:0xf bound_ctrl:1
	v_add_f32_dpp v11, v11, v11 quad_perm:[2,3,0,1] row_mask:0xf bank_mask:0xf bound_ctrl:1
	v_pk_fma_f32 v[20:21], v[4:5], v[68:69], v[20:21]
	v_add_f32_dpp v10, v10, v10 row_half_mirror row_mask:0xf bank_mask:0xf bound_ctrl:1
	v_add_f32_dpp v11, v11, v11 row_half_mirror row_mask:0xf bank_mask:0xf bound_ctrl:1
	s_nop 0
	v_add_f32_dpp v10, v10, v10 row_mirror row_mask:0xf bank_mask:0xf bound_ctrl:1
	v_add_f32_dpp v11, v11, v11 row_mirror row_mask:0xf bank_mask:0xf bound_ctrl:1
	v_pk_fma_f32 v[2:3], v[70:71], v[10:11], v[18:19] op_sel_hi:[1,0,1]
	v_pk_fma_f32 v[4:5], v[72:73], v[10:11], v[20:21] op_sel_hi:[1,0,1]
	v_fmac_f32_e32 v11, v120, v10
	v_fmac_f32_e32 v11, v118, v121
	s_waitcnt lgkmcnt(13)
	ds_read_b64 v[186:187], v6 offset:8960
	ds_read_b64 v[188:189], v6 offset:8968
	ds_read_b64 v[190:191], v6 offset:8976
	ds_read_b64 v[192:193], v6 offset:8984
	ds_read_b64 v[194:195], v6 offset:8992
	ds_read_b64 v[196:197], v6 offset:9000
	ds_read_b64 v[198:199], v6 offset:9008
	ds_read_b64 v[200:201], v6 offset:9016
	ds_read_b64 v[202:203], v6 offset:9024
	ds_read_b64 v[204:205], v6 offset:9032
	v_pk_mul_f32 v[12:13], v[2:3], v[78:79] op_sel_hi:[0,1]
	v_pk_fma_f32 v[12:13], v[2:3], v[80:81], v[12:13] op_sel:[1,0,0] op_sel_hi:[1,1,1]
	v_pk_fma_f32 v[12:13], v[4:5], v[82:83], v[12:13] op_sel_hi:[0,1,1]
	v_pk_fma_f32 v[12:13], v[4:5], v[84:85], v[12:13] op_sel:[1,0,0] op_sel_hi:[1,1,1]
	v_pk_mul_f32 v[18:19], v[94:95], v[118:119] op_sel:[0,1] op_sel_hi:[1,1]
	v_pk_mul_f32 v[20:21], v[96:97], v[118:119] op_sel:[0,1] op_sel_hi:[1,1]
	v_add_f32_dpp v12, v12, v12 quad_perm:[1,0,3,2] row_mask:0xf bank_mask:0xf bound_ctrl:1
	v_add_f32_dpp v13, v13, v13 quad_perm:[1,0,3,2] row_mask:0xf bank_mask:0xf bound_ctrl:1
	v_pk_fma_f32 v[18:19], v[2:3], v[86:87], v[18:19]
	v_add_f32_dpp v12, v12, v12 quad_perm:[2,3,0,1] row_mask:0xf bank_mask:0xf bound_ctrl:1
	v_add_f32_dpp v13, v13, v13 quad_perm:[2,3,0,1] row_mask:0xf bank_mask:0xf bound_ctrl:1
	v_pk_fma_f32 v[20:21], v[4:5], v[88:89], v[20:21]
	v_add_f32_dpp v12, v12, v12 row_half_mirror row_mask:0xf bank_mask:0xf bound_ctrl:1
	v_add_f32_dpp v13, v13, v13 row_half_mirror row_mask:0xf bank_mask:0xf bound_ctrl:1
	s_nop 0
	v_add_f32_dpp v12, v12, v12 row_mirror row_mask:0xf bank_mask:0xf bound_ctrl:1
	v_add_f32_dpp v13, v13, v13 row_mirror row_mask:0xf bank_mask:0xf bound_ctrl:1
	v_pk_fma_f32 v[2:3], v[90:91], v[12:13], v[18:19] op_sel_hi:[1,0,1]
	v_pk_fma_f32 v[4:5], v[92:93], v[12:13], v[20:21] op_sel_hi:[1,0,1]
	v_fmac_f32_e32 v13, v122, v12
	v_fmac_f32_e32 v13, v119, v123
	ds_write2_b32 v9, v11, v13 offset0:64 offset1:80
	s_waitcnt lgkmcnt(11)
	ds_read_b64 v[58:59], v6 offset:10240
	ds_read_b64 v[60:61], v6 offset:10248
	ds_read_b64 v[62:63], v6 offset:10256
	ds_read_b64 v[64:65], v6 offset:10264
	ds_read_b64 v[66:67], v6 offset:10272
	ds_read_b64 v[68:69], v6 offset:10280
	ds_read_b64 v[70:71], v6 offset:10288
	ds_read_b64 v[72:73], v6 offset:10296
	ds_read_b64 v[74:75], v6 offset:10304
	ds_read_b64 v[76:77], v6 offset:10312
	ds_read2st64_b32 v[118:119], v7 offset0:8 offset1:9
	ds_read_b128 v[120:123], v8 offset:64
	v_pk_mul_f32 v[14:15], v[2:3], v[98:99] op_sel_hi:[0,1]
	v_pk_fma_f32 v[14:15], v[2:3], v[100:101], v[14:15] op_sel:[1,0,0] op_sel_hi:[1,1,1]
	v_pk_fma_f32 v[14:15], v[4:5], v[102:103], v[14:15] op_sel_hi:[0,1,1]
	v_pk_fma_f32 v[14:15], v[4:5], v[104:105], v[14:15] op_sel:[1,0,0] op_sel_hi:[1,1,1]
	v_pk_mul_f32 v[18:19], v[114:115], v[206:207] op_sel_hi:[1,0]
	v_pk_mul_f32 v[20:21], v[116:117], v[206:207] op_sel_hi:[1,0]
	v_add_f32_dpp v14, v14, v14 quad_perm:[1,0,3,2] row_mask:0xf bank_mask:0xf bound_ctrl:1
	v_add_f32_dpp v15, v15, v15 quad_perm:[1,0,3,2] row_mask:0xf bank_mask:0xf bound_ctrl:1
	v_pk_fma_f32 v[18:19], v[2:3], v[106:107], v[18:19]
	v_add_f32_dpp v14, v14, v14 quad_perm:[2,3,0,1] row_mask:0xf bank_mask:0xf bound_ctrl:1
	v_add_f32_dpp v15, v15, v15 quad_perm:[2,3,0,1] row_mask:0xf bank_mask:0xf bound_ctrl:1
	v_pk_fma_f32 v[20:21], v[4:5], v[108:109], v[20:21]
	v_add_f32_dpp v14, v14, v14 row_half_mirror row_mask:0xf bank_mask:0xf bound_ctrl:1
	v_add_f32_dpp v15, v15, v15 row_half_mirror row_mask:0xf bank_mask:0xf bound_ctrl:1
	s_nop 0
	v_add_f32_dpp v14, v14, v14 row_mirror row_mask:0xf bank_mask:0xf bound_ctrl:1
	v_add_f32_dpp v15, v15, v15 row_mirror row_mask:0xf bank_mask:0xf bound_ctrl:1
	v_pk_fma_f32 v[2:3], v[110:111], v[14:15], v[18:19] op_sel_hi:[1,0,1]
	v_pk_fma_f32 v[4:5], v[112:113], v[14:15], v[20:21] op_sel_hi:[1,0,1]
	v_fmac_f32_e32 v15, v208, v14
	v_fmac_f32_e32 v15, v206, v209
	s_waitcnt lgkmcnt(13)
	ds_read_b64 v[78:79], v6 offset:11520
	ds_read_b64 v[80:81], v6 offset:11528
	ds_read_b64 v[82:83], v6 offset:11536
	ds_read_b64 v[84:85], v6 offset:11544
	ds_read_b64 v[86:87], v6 offset:11552
	ds_read_b64 v[88:89], v6 offset:11560
	ds_read_b64 v[90:91], v6 offset:11568
	ds_read_b64 v[92:93], v6 offset:11576
	ds_read_b64 v[94:95], v6 offset:11584
	ds_read_b64 v[96:97], v6 offset:11592
	v_pk_mul_f32 v[16:17], v[2:3], v[186:187] op_sel_hi:[0,1]
	v_pk_fma_f32 v[16:17], v[2:3], v[188:189], v[16:17] op_sel:[1,0,0] op_sel_hi:[1,1,1]
	v_pk_fma_f32 v[16:17], v[4:5], v[190:191], v[16:17] op_sel_hi:[0,1,1]
	v_pk_fma_f32 v[16:17], v[4:5], v[192:193], v[16:17] op_sel:[1,0,0] op_sel_hi:[1,1,1]
	v_pk_mul_f32 v[18:19], v[202:203], v[206:207] op_sel:[0,1] op_sel_hi:[1,1]
	v_pk_mul_f32 v[20:21], v[204:205], v[206:207] op_sel:[0,1] op_sel_hi:[1,1]
	v_add_f32_dpp v16, v16, v16 quad_perm:[1,0,3,2] row_mask:0xf bank_mask:0xf bound_ctrl:1
	v_add_f32_dpp v17, v17, v17 quad_perm:[1,0,3,2] row_mask:0xf bank_mask:0xf bound_ctrl:1
	v_pk_fma_f32 v[18:19], v[2:3], v[194:195], v[18:19]
	v_add_f32_dpp v16, v16, v16 quad_perm:[2,3,0,1] row_mask:0xf bank_mask:0xf bound_ctrl:1
	v_add_f32_dpp v17, v17, v17 quad_perm:[2,3,0,1] row_mask:0xf bank_mask:0xf bound_ctrl:1
	v_pk_fma_f32 v[20:21], v[4:5], v[196:197], v[20:21]
	v_add_f32_dpp v16, v16, v16 row_half_mirror row_mask:0xf bank_mask:0xf bound_ctrl:1
	v_add_f32_dpp v17, v17, v17 row_half_mirror row_mask:0xf bank_mask:0xf bound_ctrl:1
	s_nop 0
	v_add_f32_dpp v16, v16, v16 row_mirror row_mask:0xf bank_mask:0xf bound_ctrl:1
	v_add_f32_dpp v17, v17, v17 row_mirror row_mask:0xf bank_mask:0xf bound_ctrl:1
	v_pk_fma_f32 v[2:3], v[198:199], v[16:17], v[18:19] op_sel_hi:[1,0,1]
	v_pk_fma_f32 v[4:5], v[200:201], v[16:17], v[20:21] op_sel_hi:[1,0,1]
	v_fmac_f32_e32 v17, v210, v16
	v_fmac_f32_e32 v17, v207, v211
	ds_write2_b32 v9, v15, v17 offset0:96 offset1:112
	s_waitcnt lgkmcnt(11)
	ds_read_b64 v[98:99], v6 offset:12800
	ds_read_b64 v[100:101], v6 offset:12808
	ds_read_b64 v[102:103], v6 offset:12816
	ds_read_b64 v[104:105], v6 offset:12824
	ds_read_b64 v[106:107], v6 offset:12832
	ds_read_b64 v[108:109], v6 offset:12840
	ds_read_b64 v[110:111], v6 offset:12848
	ds_read_b64 v[112:113], v6 offset:12856
	ds_read_b64 v[114:115], v6 offset:12864
	ds_read_b64 v[116:117], v6 offset:12872
	ds_read2st64_b32 v[206:207], v7 offset0:10 offset1:11
	ds_read_b128 v[208:211], v8 offset:80
	v_pk_mul_f32 v[10:11], v[2:3], v[58:59] op_sel_hi:[0,1]
	v_pk_fma_f32 v[10:11], v[2:3], v[60:61], v[10:11] op_sel:[1,0,0] op_sel_hi:[1,1,1]
	v_pk_fma_f32 v[10:11], v[4:5], v[62:63], v[10:11] op_sel_hi:[0,1,1]
	v_pk_fma_f32 v[10:11], v[4:5], v[64:65], v[10:11] op_sel:[1,0,0] op_sel_hi:[1,1,1]
	v_pk_mul_f32 v[18:19], v[74:75], v[118:119] op_sel_hi:[1,0]
	v_pk_mul_f32 v[20:21], v[76:77], v[118:119] op_sel_hi:[1,0]
	v_add_f32_dpp v10, v10, v10 quad_perm:[1,0,3,2] row_mask:0xf bank_mask:0xf bound_ctrl:1
	v_add_f32_dpp v11, v11, v11 quad_perm:[1,0,3,2] row_mask:0xf bank_mask:0xf bound_ctrl:1
	v_pk_fma_f32 v[18:19], v[2:3], v[66:67], v[18:19]
	v_add_f32_dpp v10, v10, v10 quad_perm:[2,3,0,1] row_mask:0xf bank_mask:0xf bound_ctrl:1
	v_add_f32_dpp v11, v11, v11 quad_perm:[2,3,0,1] row_mask:0xf bank_mask:0xf bound_ctrl:1
	v_pk_fma_f32 v[20:21], v[4:5], v[68:69], v[20:21]
	v_add_f32_dpp v10, v10, v10 row_half_mirror row_mask:0xf bank_mask:0xf bound_ctrl:1
	v_add_f32_dpp v11, v11, v11 row_half_mirror row_mask:0xf bank_mask:0xf bound_ctrl:1
	s_nop 0
	v_add_f32_dpp v10, v10, v10 row_mirror row_mask:0xf bank_mask:0xf bound_ctrl:1
	v_add_f32_dpp v11, v11, v11 row_mirror row_mask:0xf bank_mask:0xf bound_ctrl:1
	v_pk_fma_f32 v[2:3], v[70:71], v[10:11], v[18:19] op_sel_hi:[1,0,1]
	v_pk_fma_f32 v[4:5], v[72:73], v[10:11], v[20:21] op_sel_hi:[1,0,1]
	v_fmac_f32_e32 v11, v120, v10
	v_fmac_f32_e32 v11, v118, v121
	s_waitcnt lgkmcnt(13)
	ds_read_b64 v[186:187], v6 offset:14080
	ds_read_b64 v[188:189], v6 offset:14088
	ds_read_b64 v[190:191], v6 offset:14096
	ds_read_b64 v[192:193], v6 offset:14104
	ds_read_b64 v[194:195], v6 offset:14112
	ds_read_b64 v[196:197], v6 offset:14120
	ds_read_b64 v[198:199], v6 offset:14128
	ds_read_b64 v[200:201], v6 offset:14136
	ds_read_b64 v[202:203], v6 offset:14144
	ds_read_b64 v[204:205], v6 offset:14152
	v_pk_mul_f32 v[12:13], v[2:3], v[78:79] op_sel_hi:[0,1]
	v_pk_fma_f32 v[12:13], v[2:3], v[80:81], v[12:13] op_sel:[1,0,0] op_sel_hi:[1,1,1]
	v_pk_fma_f32 v[12:13], v[4:5], v[82:83], v[12:13] op_sel_hi:[0,1,1]
	v_pk_fma_f32 v[12:13], v[4:5], v[84:85], v[12:13] op_sel:[1,0,0] op_sel_hi:[1,1,1]
	v_pk_mul_f32 v[18:19], v[94:95], v[118:119] op_sel:[0,1] op_sel_hi:[1,1]
	v_pk_mul_f32 v[20:21], v[96:97], v[118:119] op_sel:[0,1] op_sel_hi:[1,1]
	v_add_f32_dpp v12, v12, v12 quad_perm:[1,0,3,2] row_mask:0xf bank_mask:0xf bound_ctrl:1
	v_add_f32_dpp v13, v13, v13 quad_perm:[1,0,3,2] row_mask:0xf bank_mask:0xf bound_ctrl:1
	v_pk_fma_f32 v[18:19], v[2:3], v[86:87], v[18:19]
	v_add_f32_dpp v12, v12, v12 quad_perm:[2,3,0,1] row_mask:0xf bank_mask:0xf bound_ctrl:1
	v_add_f32_dpp v13, v13, v13 quad_perm:[2,3,0,1] row_mask:0xf bank_mask:0xf bound_ctrl:1
	v_pk_fma_f32 v[20:21], v[4:5], v[88:89], v[20:21]
	v_add_f32_dpp v12, v12, v12 row_half_mirror row_mask:0xf bank_mask:0xf bound_ctrl:1
	v_add_f32_dpp v13, v13, v13 row_half_mirror row_mask:0xf bank_mask:0xf bound_ctrl:1
	s_nop 0
	v_add_f32_dpp v12, v12, v12 row_mirror row_mask:0xf bank_mask:0xf bound_ctrl:1
	v_add_f32_dpp v13, v13, v13 row_mirror row_mask:0xf bank_mask:0xf bound_ctrl:1
	v_pk_fma_f32 v[2:3], v[90:91], v[12:13], v[18:19] op_sel_hi:[1,0,1]
	v_pk_fma_f32 v[4:5], v[92:93], v[12:13], v[20:21] op_sel_hi:[1,0,1]
	v_fmac_f32_e32 v13, v122, v12
	v_fmac_f32_e32 v13, v119, v123
	ds_write2_b32 v9, v11, v13 offset0:128 offset1:144
	s_waitcnt lgkmcnt(11)
	ds_read_b64 v[58:59], v6 offset:15360
	ds_read_b64 v[60:61], v6 offset:15368
	ds_read_b64 v[62:63], v6 offset:15376
	ds_read_b64 v[64:65], v6 offset:15384
	ds_read_b64 v[66:67], v6 offset:15392
	ds_read_b64 v[68:69], v6 offset:15400
	ds_read_b64 v[70:71], v6 offset:15408
	ds_read_b64 v[72:73], v6 offset:15416
	ds_read_b64 v[74:75], v6 offset:15424
	ds_read_b64 v[76:77], v6 offset:15432
	ds_read2st64_b32 v[118:119], v7 offset0:12 offset1:13
	ds_read_b128 v[120:123], v8 offset:96
	v_pk_mul_f32 v[14:15], v[2:3], v[98:99] op_sel_hi:[0,1]
	v_pk_fma_f32 v[14:15], v[2:3], v[100:101], v[14:15] op_sel:[1,0,0] op_sel_hi:[1,1,1]
	v_pk_fma_f32 v[14:15], v[4:5], v[102:103], v[14:15] op_sel_hi:[0,1,1]
	v_pk_fma_f32 v[14:15], v[4:5], v[104:105], v[14:15] op_sel:[1,0,0] op_sel_hi:[1,1,1]
	v_pk_mul_f32 v[18:19], v[114:115], v[206:207] op_sel_hi:[1,0]
	v_pk_mul_f32 v[20:21], v[116:117], v[206:207] op_sel_hi:[1,0]
	v_add_f32_dpp v14, v14, v14 quad_perm:[1,0,3,2] row_mask:0xf bank_mask:0xf bound_ctrl:1
	v_add_f32_dpp v15, v15, v15 quad_perm:[1,0,3,2] row_mask:0xf bank_mask:0xf bound_ctrl:1
	v_pk_fma_f32 v[18:19], v[2:3], v[106:107], v[18:19]
	v_add_f32_dpp v14, v14, v14 quad_perm:[2,3,0,1] row_mask:0xf bank_mask:0xf bound_ctrl:1
	v_add_f32_dpp v15, v15, v15 quad_perm:[2,3,0,1] row_mask:0xf bank_mask:0xf bound_ctrl:1
	v_pk_fma_f32 v[20:21], v[4:5], v[108:109], v[20:21]
	v_add_f32_dpp v14, v14, v14 row_half_mirror row_mask:0xf bank_mask:0xf bound_ctrl:1
	v_add_f32_dpp v15, v15, v15 row_half_mirror row_mask:0xf bank_mask:0xf bound_ctrl:1
	s_nop 0
	v_add_f32_dpp v14, v14, v14 row_mirror row_mask:0xf bank_mask:0xf bound_ctrl:1
	v_add_f32_dpp v15, v15, v15 row_mirror row_mask:0xf bank_mask:0xf bound_ctrl:1
	v_pk_fma_f32 v[2:3], v[110:111], v[14:15], v[18:19] op_sel_hi:[1,0,1]
	v_pk_fma_f32 v[4:5], v[112:113], v[14:15], v[20:21] op_sel_hi:[1,0,1]
	v_fmac_f32_e32 v15, v208, v14
	v_fmac_f32_e32 v15, v206, v209
	s_waitcnt lgkmcnt(13)
	ds_read_b64 v[78:79], v6 offset:16640
	ds_read_b64 v[80:81], v6 offset:16648
	ds_read_b64 v[82:83], v6 offset:16656
	ds_read_b64 v[84:85], v6 offset:16664
	ds_read_b64 v[86:87], v6 offset:16672
	ds_read_b64 v[88:89], v6 offset:16680
	ds_read_b64 v[90:91], v6 offset:16688
	ds_read_b64 v[92:93], v6 offset:16696
	ds_read_b64 v[94:95], v6 offset:16704
	ds_read_b64 v[96:97], v6 offset:16712
	v_pk_mul_f32 v[16:17], v[2:3], v[186:187] op_sel_hi:[0,1]
	v_pk_fma_f32 v[16:17], v[2:3], v[188:189], v[16:17] op_sel:[1,0,0] op_sel_hi:[1,1,1]
	v_pk_fma_f32 v[16:17], v[4:5], v[190:191], v[16:17] op_sel_hi:[0,1,1]
	v_pk_fma_f32 v[16:17], v[4:5], v[192:193], v[16:17] op_sel:[1,0,0] op_sel_hi:[1,1,1]
	v_pk_mul_f32 v[18:19], v[202:203], v[206:207] op_sel:[0,1] op_sel_hi:[1,1]
	v_pk_mul_f32 v[20:21], v[204:205], v[206:207] op_sel:[0,1] op_sel_hi:[1,1]
	v_add_f32_dpp v16, v16, v16 quad_perm:[1,0,3,2] row_mask:0xf bank_mask:0xf bound_ctrl:1
	v_add_f32_dpp v17, v17, v17 quad_perm:[1,0,3,2] row_mask:0xf bank_mask:0xf bound_ctrl:1
	v_pk_fma_f32 v[18:19], v[2:3], v[194:195], v[18:19]
	v_add_f32_dpp v16, v16, v16 quad_perm:[2,3,0,1] row_mask:0xf bank_mask:0xf bound_ctrl:1
	v_add_f32_dpp v17, v17, v17 quad_perm:[2,3,0,1] row_mask:0xf bank_mask:0xf bound_ctrl:1
	v_pk_fma_f32 v[20:21], v[4:5], v[196:197], v[20:21]
	v_add_f32_dpp v16, v16, v16 row_half_mirror row_mask:0xf bank_mask:0xf bound_ctrl:1
	v_add_f32_dpp v17, v17, v17 row_half_mirror row_mask:0xf bank_mask:0xf bound_ctrl:1
	s_nop 0
	v_add_f32_dpp v16, v16, v16 row_mirror row_mask:0xf bank_mask:0xf bound_ctrl:1
	v_add_f32_dpp v17, v17, v17 row_mirror row_mask:0xf bank_mask:0xf bound_ctrl:1
	v_pk_fma_f32 v[2:3], v[198:199], v[16:17], v[18:19] op_sel_hi:[1,0,1]
	v_pk_fma_f32 v[4:5], v[200:201], v[16:17], v[20:21] op_sel_hi:[1,0,1]
	v_fmac_f32_e32 v17, v210, v16
	v_fmac_f32_e32 v17, v207, v211
	ds_write2_b32 v9, v15, v17 offset0:160 offset1:176
	s_waitcnt lgkmcnt(11)
	ds_read_b64 v[98:99], v6 offset:17920
	ds_read_b64 v[100:101], v6 offset:17928
	ds_read_b64 v[102:103], v6 offset:17936
	ds_read_b64 v[104:105], v6 offset:17944
	ds_read_b64 v[106:107], v6 offset:17952
	ds_read_b64 v[108:109], v6 offset:17960
	ds_read_b64 v[110:111], v6 offset:17968
	ds_read_b64 v[112:113], v6 offset:17976
	ds_read_b64 v[114:115], v6 offset:17984
	ds_read_b64 v[116:117], v6 offset:17992
	ds_read2st64_b32 v[206:207], v7 offset0:14 offset1:15
	ds_read_b128 v[208:211], v8 offset:112
	v_pk_mul_f32 v[10:11], v[2:3], v[58:59] op_sel_hi:[0,1]
	v_pk_fma_f32 v[10:11], v[2:3], v[60:61], v[10:11] op_sel:[1,0,0] op_sel_hi:[1,1,1]
	v_pk_fma_f32 v[10:11], v[4:5], v[62:63], v[10:11] op_sel_hi:[0,1,1]
	v_pk_fma_f32 v[10:11], v[4:5], v[64:65], v[10:11] op_sel:[1,0,0] op_sel_hi:[1,1,1]
	v_pk_mul_f32 v[18:19], v[74:75], v[118:119] op_sel_hi:[1,0]
	v_pk_mul_f32 v[20:21], v[76:77], v[118:119] op_sel_hi:[1,0]
	v_add_f32_dpp v10, v10, v10 quad_perm:[1,0,3,2] row_mask:0xf bank_mask:0xf bound_ctrl:1
	v_add_f32_dpp v11, v11, v11 quad_perm:[1,0,3,2] row_mask:0xf bank_mask:0xf bound_ctrl:1
	v_pk_fma_f32 v[18:19], v[2:3], v[66:67], v[18:19]
	v_add_f32_dpp v10, v10, v10 quad_perm:[2,3,0,1] row_mask:0xf bank_mask:0xf bound_ctrl:1
	v_add_f32_dpp v11, v11, v11 quad_perm:[2,3,0,1] row_mask:0xf bank_mask:0xf bound_ctrl:1
	v_pk_fma_f32 v[20:21], v[4:5], v[68:69], v[20:21]
	v_add_f32_dpp v10, v10, v10 row_half_mirror row_mask:0xf bank_mask:0xf bound_ctrl:1
	v_add_f32_dpp v11, v11, v11 row_half_mirror row_mask:0xf bank_mask:0xf bound_ctrl:1
	s_nop 0
	v_add_f32_dpp v10, v10, v10 row_mirror row_mask:0xf bank_mask:0xf bound_ctrl:1
	v_add_f32_dpp v11, v11, v11 row_mirror row_mask:0xf bank_mask:0xf bound_ctrl:1
	v_pk_fma_f32 v[2:3], v[70:71], v[10:11], v[18:19] op_sel_hi:[1,0,1]
	v_pk_fma_f32 v[4:5], v[72:73], v[10:11], v[20:21] op_sel_hi:[1,0,1]
	v_fmac_f32_e32 v11, v120, v10
	v_fmac_f32_e32 v11, v118, v121
	s_waitcnt lgkmcnt(13)
	ds_read_b64 v[186:187], v6 offset:19200
	ds_read_b64 v[188:189], v6 offset:19208
	ds_read_b64 v[190:191], v6 offset:19216
	ds_read_b64 v[192:193], v6 offset:19224
	ds_read_b64 v[194:195], v6 offset:19232
	ds_read_b64 v[196:197], v6 offset:19240
	ds_read_b64 v[198:199], v6 offset:19248
	ds_read_b64 v[200:201], v6 offset:19256
	ds_read_b64 v[202:203], v6 offset:19264
	ds_read_b64 v[204:205], v6 offset:19272
	v_pk_mul_f32 v[12:13], v[2:3], v[78:79] op_sel_hi:[0,1]
	v_pk_fma_f32 v[12:13], v[2:3], v[80:81], v[12:13] op_sel:[1,0,0] op_sel_hi:[1,1,1]
	v_pk_fma_f32 v[12:13], v[4:5], v[82:83], v[12:13] op_sel_hi:[0,1,1]
	v_pk_fma_f32 v[12:13], v[4:5], v[84:85], v[12:13] op_sel:[1,0,0] op_sel_hi:[1,1,1]
	v_pk_mul_f32 v[18:19], v[94:95], v[118:119] op_sel:[0,1] op_sel_hi:[1,1]
	v_pk_mul_f32 v[20:21], v[96:97], v[118:119] op_sel:[0,1] op_sel_hi:[1,1]
	v_add_f32_dpp v12, v12, v12 quad_perm:[1,0,3,2] row_mask:0xf bank_mask:0xf bound_ctrl:1
	v_add_f32_dpp v13, v13, v13 quad_perm:[1,0,3,2] row_mask:0xf bank_mask:0xf bound_ctrl:1
	v_pk_fma_f32 v[18:19], v[2:3], v[86:87], v[18:19]
	v_add_f32_dpp v12, v12, v12 quad_perm:[2,3,0,1] row_mask:0xf bank_mask:0xf bound_ctrl:1
	v_add_f32_dpp v13, v13, v13 quad_perm:[2,3,0,1] row_mask:0xf bank_mask:0xf bound_ctrl:1
	v_pk_fma_f32 v[20:21], v[4:5], v[88:89], v[20:21]
	v_add_f32_dpp v12, v12, v12 row_half_mirror row_mask:0xf bank_mask:0xf bound_ctrl:1
	v_add_f32_dpp v13, v13, v13 row_half_mirror row_mask:0xf bank_mask:0xf bound_ctrl:1
	s_nop 0
	v_add_f32_dpp v12, v12, v12 row_mirror row_mask:0xf bank_mask:0xf bound_ctrl:1
	v_add_f32_dpp v13, v13, v13 row_mirror row_mask:0xf bank_mask:0xf bound_ctrl:1
	v_pk_fma_f32 v[2:3], v[90:91], v[12:13], v[18:19] op_sel_hi:[1,0,1]
	v_pk_fma_f32 v[4:5], v[92:93], v[12:13], v[20:21] op_sel_hi:[1,0,1]
	v_fmac_f32_e32 v13, v122, v12
	v_fmac_f32_e32 v13, v119, v123
	ds_write2_b32 v9, v11, v13 offset0:192 offset1:208
	s_waitcnt lgkmcnt(11)
	ds_read_b64 v[58:59], v6 offset:20480
	ds_read_b64 v[60:61], v6 offset:20488
	ds_read_b64 v[62:63], v6 offset:20496
	ds_read_b64 v[64:65], v6 offset:20504
	ds_read_b64 v[66:67], v6 offset:20512
	ds_read_b64 v[68:69], v6 offset:20520
	ds_read_b64 v[70:71], v6 offset:20528
	ds_read_b64 v[72:73], v6 offset:20536
	ds_read_b64 v[74:75], v6 offset:20544
	ds_read_b64 v[76:77], v6 offset:20552
	ds_read2st64_b32 v[118:119], v7 offset0:16 offset1:17
	ds_read_b128 v[120:123], v8 offset:128
	v_pk_mul_f32 v[14:15], v[2:3], v[98:99] op_sel_hi:[0,1]
	v_pk_fma_f32 v[14:15], v[2:3], v[100:101], v[14:15] op_sel:[1,0,0] op_sel_hi:[1,1,1]
	v_pk_fma_f32 v[14:15], v[4:5], v[102:103], v[14:15] op_sel_hi:[0,1,1]
	v_pk_fma_f32 v[14:15], v[4:5], v[104:105], v[14:15] op_sel:[1,0,0] op_sel_hi:[1,1,1]
	v_pk_mul_f32 v[18:19], v[114:115], v[206:207] op_sel_hi:[1,0]
	v_pk_mul_f32 v[20:21], v[116:117], v[206:207] op_sel_hi:[1,0]
	v_add_f32_dpp v14, v14, v14 quad_perm:[1,0,3,2] row_mask:0xf bank_mask:0xf bound_ctrl:1
	v_add_f32_dpp v15, v15, v15 quad_perm:[1,0,3,2] row_mask:0xf bank_mask:0xf bound_ctrl:1
	v_pk_fma_f32 v[18:19], v[2:3], v[106:107], v[18:19]
	v_add_f32_dpp v14, v14, v14 quad_perm:[2,3,0,1] row_mask:0xf bank_mask:0xf bound_ctrl:1
	v_add_f32_dpp v15, v15, v15 quad_perm:[2,3,0,1] row_mask:0xf bank_mask:0xf bound_ctrl:1
	v_pk_fma_f32 v[20:21], v[4:5], v[108:109], v[20:21]
	v_add_f32_dpp v14, v14, v14 row_half_mirror row_mask:0xf bank_mask:0xf bound_ctrl:1
	v_add_f32_dpp v15, v15, v15 row_half_mirror row_mask:0xf bank_mask:0xf bound_ctrl:1
	s_nop 0
	v_add_f32_dpp v14, v14, v14 row_mirror row_mask:0xf bank_mask:0xf bound_ctrl:1
	v_add_f32_dpp v15, v15, v15 row_mirror row_mask:0xf bank_mask:0xf bound_ctrl:1
	v_pk_fma_f32 v[2:3], v[110:111], v[14:15], v[18:19] op_sel_hi:[1,0,1]
	v_pk_fma_f32 v[4:5], v[112:113], v[14:15], v[20:21] op_sel_hi:[1,0,1]
	v_fmac_f32_e32 v15, v208, v14
	v_fmac_f32_e32 v15, v206, v209
	s_waitcnt lgkmcnt(13)
	ds_read_b64 v[78:79], v6 offset:21760
	ds_read_b64 v[80:81], v6 offset:21768
	ds_read_b64 v[82:83], v6 offset:21776
	ds_read_b64 v[84:85], v6 offset:21784
	ds_read_b64 v[86:87], v6 offset:21792
	ds_read_b64 v[88:89], v6 offset:21800
	ds_read_b64 v[90:91], v6 offset:21808
	ds_read_b64 v[92:93], v6 offset:21816
	ds_read_b64 v[94:95], v6 offset:21824
	ds_read_b64 v[96:97], v6 offset:21832
	v_pk_mul_f32 v[16:17], v[2:3], v[186:187] op_sel_hi:[0,1]
	v_pk_fma_f32 v[16:17], v[2:3], v[188:189], v[16:17] op_sel:[1,0,0] op_sel_hi:[1,1,1]
	v_pk_fma_f32 v[16:17], v[4:5], v[190:191], v[16:17] op_sel_hi:[0,1,1]
	v_pk_fma_f32 v[16:17], v[4:5], v[192:193], v[16:17] op_sel:[1,0,0] op_sel_hi:[1,1,1]
	v_pk_mul_f32 v[18:19], v[202:203], v[206:207] op_sel:[0,1] op_sel_hi:[1,1]
	v_pk_mul_f32 v[20:21], v[204:205], v[206:207] op_sel:[0,1] op_sel_hi:[1,1]
	v_add_f32_dpp v16, v16, v16 quad_perm:[1,0,3,2] row_mask:0xf bank_mask:0xf bound_ctrl:1
	v_add_f32_dpp v17, v17, v17 quad_perm:[1,0,3,2] row_mask:0xf bank_mask:0xf bound_ctrl:1
	v_pk_fma_f32 v[18:19], v[2:3], v[194:195], v[18:19]
	v_add_f32_dpp v16, v16, v16 quad_perm:[2,3,0,1] row_mask:0xf bank_mask:0xf bound_ctrl:1
	v_add_f32_dpp v17, v17, v17 quad_perm:[2,3,0,1] row_mask:0xf bank_mask:0xf bound_ctrl:1
	v_pk_fma_f32 v[20:21], v[4:5], v[196:197], v[20:21]
	v_add_f32_dpp v16, v16, v16 row_half_mirror row_mask:0xf bank_mask:0xf bound_ctrl:1
	v_add_f32_dpp v17, v17, v17 row_half_mirror row_mask:0xf bank_mask:0xf bound_ctrl:1
	s_nop 0
	v_add_f32_dpp v16, v16, v16 row_mirror row_mask:0xf bank_mask:0xf bound_ctrl:1
	v_add_f32_dpp v17, v17, v17 row_mirror row_mask:0xf bank_mask:0xf bound_ctrl:1
	v_pk_fma_f32 v[2:3], v[198:199], v[16:17], v[18:19] op_sel_hi:[1,0,1]
	v_pk_fma_f32 v[4:5], v[200:201], v[16:17], v[20:21] op_sel_hi:[1,0,1]
	v_fmac_f32_e32 v17, v210, v16
	v_fmac_f32_e32 v17, v207, v211
	ds_write2_b32 v9, v15, v17 offset0:224 offset1:240
	s_waitcnt lgkmcnt(11)
	ds_read_b64 v[98:99], v6 offset:23040
	ds_read_b64 v[100:101], v6 offset:23048
	ds_read_b64 v[102:103], v6 offset:23056
	ds_read_b64 v[104:105], v6 offset:23064
	ds_read_b64 v[106:107], v6 offset:23072
	ds_read_b64 v[108:109], v6 offset:23080
	ds_read_b64 v[110:111], v6 offset:23088
	ds_read_b64 v[112:113], v6 offset:23096
	ds_read_b64 v[114:115], v6 offset:23104
	ds_read_b64 v[116:117], v6 offset:23112
	ds_read2st64_b32 v[206:207], v7 offset0:18 offset1:19
	ds_read_b128 v[208:211], v8 offset:144
	v_pk_mul_f32 v[10:11], v[2:3], v[58:59] op_sel_hi:[0,1]
	v_pk_fma_f32 v[10:11], v[2:3], v[60:61], v[10:11] op_sel:[1,0,0] op_sel_hi:[1,1,1]
	v_pk_fma_f32 v[10:11], v[4:5], v[62:63], v[10:11] op_sel_hi:[0,1,1]
	v_pk_fma_f32 v[10:11], v[4:5], v[64:65], v[10:11] op_sel:[1,0,0] op_sel_hi:[1,1,1]
	v_pk_mul_f32 v[18:19], v[74:75], v[118:119] op_sel_hi:[1,0]
	v_pk_mul_f32 v[20:21], v[76:77], v[118:119] op_sel_hi:[1,0]
	v_add_f32_dpp v10, v10, v10 quad_perm:[1,0,3,2] row_mask:0xf bank_mask:0xf bound_ctrl:1
	v_add_f32_dpp v11, v11, v11 quad_perm:[1,0,3,2] row_mask:0xf bank_mask:0xf bound_ctrl:1
	v_pk_fma_f32 v[18:19], v[2:3], v[66:67], v[18:19]
	v_add_f32_dpp v10, v10, v10 quad_perm:[2,3,0,1] row_mask:0xf bank_mask:0xf bound_ctrl:1
	v_add_f32_dpp v11, v11, v11 quad_perm:[2,3,0,1] row_mask:0xf bank_mask:0xf bound_ctrl:1
	v_pk_fma_f32 v[20:21], v[4:5], v[68:69], v[20:21]
	v_add_f32_dpp v10, v10, v10 row_half_mirror row_mask:0xf bank_mask:0xf bound_ctrl:1
	v_add_f32_dpp v11, v11, v11 row_half_mirror row_mask:0xf bank_mask:0xf bound_ctrl:1
	s_nop 0
	v_add_f32_dpp v10, v10, v10 row_mirror row_mask:0xf bank_mask:0xf bound_ctrl:1
	v_add_f32_dpp v11, v11, v11 row_mirror row_mask:0xf bank_mask:0xf bound_ctrl:1
	v_pk_fma_f32 v[2:3], v[70:71], v[10:11], v[18:19] op_sel_hi:[1,0,1]
	v_pk_fma_f32 v[4:5], v[72:73], v[10:11], v[20:21] op_sel_hi:[1,0,1]
	v_fmac_f32_e32 v11, v120, v10
	v_fmac_f32_e32 v11, v118, v121
	s_waitcnt lgkmcnt(13)
	ds_read_b64 v[186:187], v6 offset:24320
	ds_read_b64 v[188:189], v6 offset:24328
	ds_read_b64 v[190:191], v6 offset:24336
	ds_read_b64 v[192:193], v6 offset:24344
	ds_read_b64 v[194:195], v6 offset:24352
	ds_read_b64 v[196:197], v6 offset:24360
	ds_read_b64 v[198:199], v6 offset:24368
	ds_read_b64 v[200:201], v6 offset:24376
	ds_read_b64 v[202:203], v6 offset:24384
	ds_read_b64 v[204:205], v6 offset:24392
	v_pk_mul_f32 v[12:13], v[2:3], v[78:79] op_sel_hi:[0,1]
	v_pk_fma_f32 v[12:13], v[2:3], v[80:81], v[12:13] op_sel:[1,0,0] op_sel_hi:[1,1,1]
	v_pk_fma_f32 v[12:13], v[4:5], v[82:83], v[12:13] op_sel_hi:[0,1,1]
	v_pk_fma_f32 v[12:13], v[4:5], v[84:85], v[12:13] op_sel:[1,0,0] op_sel_hi:[1,1,1]
	v_pk_mul_f32 v[18:19], v[94:95], v[118:119] op_sel:[0,1] op_sel_hi:[1,1]
	v_pk_mul_f32 v[20:21], v[96:97], v[118:119] op_sel:[0,1] op_sel_hi:[1,1]
	v_add_f32_dpp v12, v12, v12 quad_perm:[1,0,3,2] row_mask:0xf bank_mask:0xf bound_ctrl:1
	v_add_f32_dpp v13, v13, v13 quad_perm:[1,0,3,2] row_mask:0xf bank_mask:0xf bound_ctrl:1
	v_pk_fma_f32 v[18:19], v[2:3], v[86:87], v[18:19]
	v_add_f32_dpp v12, v12, v12 quad_perm:[2,3,0,1] row_mask:0xf bank_mask:0xf bound_ctrl:1
	v_add_f32_dpp v13, v13, v13 quad_perm:[2,3,0,1] row_mask:0xf bank_mask:0xf bound_ctrl:1
	v_pk_fma_f32 v[20:21], v[4:5], v[88:89], v[20:21]
	v_add_f32_dpp v12, v12, v12 row_half_mirror row_mask:0xf bank_mask:0xf bound_ctrl:1
	v_add_f32_dpp v13, v13, v13 row_half_mirror row_mask:0xf bank_mask:0xf bound_ctrl:1
	s_nop 0
	v_add_f32_dpp v12, v12, v12 row_mirror row_mask:0xf bank_mask:0xf bound_ctrl:1
	v_add_f32_dpp v13, v13, v13 row_mirror row_mask:0xf bank_mask:0xf bound_ctrl:1
	v_pk_fma_f32 v[2:3], v[90:91], v[12:13], v[18:19] op_sel_hi:[1,0,1]
	v_pk_fma_f32 v[4:5], v[92:93], v[12:13], v[20:21] op_sel_hi:[1,0,1]
	v_fmac_f32_e32 v13, v122, v12
	v_fmac_f32_e32 v13, v119, v123
	ds_write2_b32 v22, v11, v13 offset1:16
	s_waitcnt lgkmcnt(11)
	ds_read_b64 v[58:59], v6 offset:25600
	ds_read_b64 v[60:61], v6 offset:25608
	ds_read_b64 v[62:63], v6 offset:25616
	ds_read_b64 v[64:65], v6 offset:25624
	ds_read_b64 v[66:67], v6 offset:25632
	ds_read_b64 v[68:69], v6 offset:25640
	ds_read_b64 v[70:71], v6 offset:25648
	ds_read_b64 v[72:73], v6 offset:25656
	ds_read_b64 v[74:75], v6 offset:25664
	ds_read_b64 v[76:77], v6 offset:25672
	ds_read2st64_b32 v[118:119], v7 offset0:20 offset1:21
	ds_read_b128 v[120:123], v8 offset:160
	v_pk_mul_f32 v[14:15], v[2:3], v[98:99] op_sel_hi:[0,1]
	v_pk_fma_f32 v[14:15], v[2:3], v[100:101], v[14:15] op_sel:[1,0,0] op_sel_hi:[1,1,1]
	v_pk_fma_f32 v[14:15], v[4:5], v[102:103], v[14:15] op_sel_hi:[0,1,1]
	v_pk_fma_f32 v[14:15], v[4:5], v[104:105], v[14:15] op_sel:[1,0,0] op_sel_hi:[1,1,1]
	v_pk_mul_f32 v[18:19], v[114:115], v[206:207] op_sel_hi:[1,0]
	v_pk_mul_f32 v[20:21], v[116:117], v[206:207] op_sel_hi:[1,0]
	v_add_f32_dpp v14, v14, v14 quad_perm:[1,0,3,2] row_mask:0xf bank_mask:0xf bound_ctrl:1
	v_add_f32_dpp v15, v15, v15 quad_perm:[1,0,3,2] row_mask:0xf bank_mask:0xf bound_ctrl:1
	v_pk_fma_f32 v[18:19], v[2:3], v[106:107], v[18:19]
	v_add_f32_dpp v14, v14, v14 quad_perm:[2,3,0,1] row_mask:0xf bank_mask:0xf bound_ctrl:1
	v_add_f32_dpp v15, v15, v15 quad_perm:[2,3,0,1] row_mask:0xf bank_mask:0xf bound_ctrl:1
	v_pk_fma_f32 v[20:21], v[4:5], v[108:109], v[20:21]
	v_add_f32_dpp v14, v14, v14 row_half_mirror row_mask:0xf bank_mask:0xf bound_ctrl:1
	v_add_f32_dpp v15, v15, v15 row_half_mirror row_mask:0xf bank_mask:0xf bound_ctrl:1
	s_nop 0
	v_add_f32_dpp v14, v14, v14 row_mirror row_mask:0xf bank_mask:0xf bound_ctrl:1
	v_add_f32_dpp v15, v15, v15 row_mirror row_mask:0xf bank_mask:0xf bound_ctrl:1
	v_pk_fma_f32 v[2:3], v[110:111], v[14:15], v[18:19] op_sel_hi:[1,0,1]
	v_pk_fma_f32 v[4:5], v[112:113], v[14:15], v[20:21] op_sel_hi:[1,0,1]
	v_fmac_f32_e32 v15, v208, v14
	v_fmac_f32_e32 v15, v206, v209
	s_waitcnt lgkmcnt(13)
	ds_read_b64 v[78:79], v6 offset:26880
	ds_read_b64 v[80:81], v6 offset:26888
	ds_read_b64 v[82:83], v6 offset:26896
	ds_read_b64 v[84:85], v6 offset:26904
	ds_read_b64 v[86:87], v6 offset:26912
	ds_read_b64 v[88:89], v6 offset:26920
	ds_read_b64 v[90:91], v6 offset:26928
	ds_read_b64 v[92:93], v6 offset:26936
	ds_read_b64 v[94:95], v6 offset:26944
	ds_read_b64 v[96:97], v6 offset:26952
	v_pk_mul_f32 v[16:17], v[2:3], v[186:187] op_sel_hi:[0,1]
	v_pk_fma_f32 v[16:17], v[2:3], v[188:189], v[16:17] op_sel:[1,0,0] op_sel_hi:[1,1,1]
	v_pk_fma_f32 v[16:17], v[4:5], v[190:191], v[16:17] op_sel_hi:[0,1,1]
	v_pk_fma_f32 v[16:17], v[4:5], v[192:193], v[16:17] op_sel:[1,0,0] op_sel_hi:[1,1,1]
	v_pk_mul_f32 v[18:19], v[202:203], v[206:207] op_sel:[0,1] op_sel_hi:[1,1]
	v_pk_mul_f32 v[20:21], v[204:205], v[206:207] op_sel:[0,1] op_sel_hi:[1,1]
	v_add_f32_dpp v16, v16, v16 quad_perm:[1,0,3,2] row_mask:0xf bank_mask:0xf bound_ctrl:1
	v_add_f32_dpp v17, v17, v17 quad_perm:[1,0,3,2] row_mask:0xf bank_mask:0xf bound_ctrl:1
	v_pk_fma_f32 v[18:19], v[2:3], v[194:195], v[18:19]
	v_add_f32_dpp v16, v16, v16 quad_perm:[2,3,0,1] row_mask:0xf bank_mask:0xf bound_ctrl:1
	v_add_f32_dpp v17, v17, v17 quad_perm:[2,3,0,1] row_mask:0xf bank_mask:0xf bound_ctrl:1
	v_pk_fma_f32 v[20:21], v[4:5], v[196:197], v[20:21]
	v_add_f32_dpp v16, v16, v16 row_half_mirror row_mask:0xf bank_mask:0xf bound_ctrl:1
	v_add_f32_dpp v17, v17, v17 row_half_mirror row_mask:0xf bank_mask:0xf bound_ctrl:1
	s_nop 0
	v_add_f32_dpp v16, v16, v16 row_mirror row_mask:0xf bank_mask:0xf bound_ctrl:1
	v_add_f32_dpp v17, v17, v17 row_mirror row_mask:0xf bank_mask:0xf bound_ctrl:1
	v_pk_fma_f32 v[2:3], v[198:199], v[16:17], v[18:19] op_sel_hi:[1,0,1]
	v_pk_fma_f32 v[4:5], v[200:201], v[16:17], v[20:21] op_sel_hi:[1,0,1]
	v_fmac_f32_e32 v17, v210, v16
	v_fmac_f32_e32 v17, v207, v211
	ds_write2_b32 v22, v15, v17 offset0:32 offset1:48
	s_waitcnt lgkmcnt(11)
	ds_read_b64 v[98:99], v6 offset:28160
	ds_read_b64 v[100:101], v6 offset:28168
	ds_read_b64 v[102:103], v6 offset:28176
	ds_read_b64 v[104:105], v6 offset:28184
	ds_read_b64 v[106:107], v6 offset:28192
	ds_read_b64 v[108:109], v6 offset:28200
	ds_read_b64 v[110:111], v6 offset:28208
	ds_read_b64 v[112:113], v6 offset:28216
	ds_read_b64 v[114:115], v6 offset:28224
	ds_read_b64 v[116:117], v6 offset:28232
	ds_read2st64_b32 v[206:207], v7 offset0:22 offset1:23
	ds_read_b128 v[208:211], v8 offset:176
	v_pk_mul_f32 v[10:11], v[2:3], v[58:59] op_sel_hi:[0,1]
	v_pk_fma_f32 v[10:11], v[2:3], v[60:61], v[10:11] op_sel:[1,0,0] op_sel_hi:[1,1,1]
	v_pk_fma_f32 v[10:11], v[4:5], v[62:63], v[10:11] op_sel_hi:[0,1,1]
	v_pk_fma_f32 v[10:11], v[4:5], v[64:65], v[10:11] op_sel:[1,0,0] op_sel_hi:[1,1,1]
	v_pk_mul_f32 v[18:19], v[74:75], v[118:119] op_sel_hi:[1,0]
	v_pk_mul_f32 v[20:21], v[76:77], v[118:119] op_sel_hi:[1,0]
	v_add_f32_dpp v10, v10, v10 quad_perm:[1,0,3,2] row_mask:0xf bank_mask:0xf bound_ctrl:1
	v_add_f32_dpp v11, v11, v11 quad_perm:[1,0,3,2] row_mask:0xf bank_mask:0xf bound_ctrl:1
	v_pk_fma_f32 v[18:19], v[2:3], v[66:67], v[18:19]
	v_add_f32_dpp v10, v10, v10 quad_perm:[2,3,0,1] row_mask:0xf bank_mask:0xf bound_ctrl:1
	v_add_f32_dpp v11, v11, v11 quad_perm:[2,3,0,1] row_mask:0xf bank_mask:0xf bound_ctrl:1
	v_pk_fma_f32 v[20:21], v[4:5], v[68:69], v[20:21]
	v_add_f32_dpp v10, v10, v10 row_half_mirror row_mask:0xf bank_mask:0xf bound_ctrl:1
	v_add_f32_dpp v11, v11, v11 row_half_mirror row_mask:0xf bank_mask:0xf bound_ctrl:1
	s_nop 0
	v_add_f32_dpp v10, v10, v10 row_mirror row_mask:0xf bank_mask:0xf bound_ctrl:1
	v_add_f32_dpp v11, v11, v11 row_mirror row_mask:0xf bank_mask:0xf bound_ctrl:1
	v_pk_fma_f32 v[2:3], v[70:71], v[10:11], v[18:19] op_sel_hi:[1,0,1]
	v_pk_fma_f32 v[4:5], v[72:73], v[10:11], v[20:21] op_sel_hi:[1,0,1]
	v_fmac_f32_e32 v11, v120, v10
	v_fmac_f32_e32 v11, v118, v121
	s_waitcnt lgkmcnt(13)
	ds_read_b64 v[186:187], v6 offset:29440
	ds_read_b64 v[188:189], v6 offset:29448
	ds_read_b64 v[190:191], v6 offset:29456
	ds_read_b64 v[192:193], v6 offset:29464
	ds_read_b64 v[194:195], v6 offset:29472
	ds_read_b64 v[196:197], v6 offset:29480
	ds_read_b64 v[198:199], v6 offset:29488
	ds_read_b64 v[200:201], v6 offset:29496
	ds_read_b64 v[202:203], v6 offset:29504
	ds_read_b64 v[204:205], v6 offset:29512
	v_pk_mul_f32 v[12:13], v[2:3], v[78:79] op_sel_hi:[0,1]
	v_pk_fma_f32 v[12:13], v[2:3], v[80:81], v[12:13] op_sel:[1,0,0] op_sel_hi:[1,1,1]
	v_pk_fma_f32 v[12:13], v[4:5], v[82:83], v[12:13] op_sel_hi:[0,1,1]
	v_pk_fma_f32 v[12:13], v[4:5], v[84:85], v[12:13] op_sel:[1,0,0] op_sel_hi:[1,1,1]
	v_pk_mul_f32 v[18:19], v[94:95], v[118:119] op_sel:[0,1] op_sel_hi:[1,1]
	v_pk_mul_f32 v[20:21], v[96:97], v[118:119] op_sel:[0,1] op_sel_hi:[1,1]
	v_add_f32_dpp v12, v12, v12 quad_perm:[1,0,3,2] row_mask:0xf bank_mask:0xf bound_ctrl:1
	v_add_f32_dpp v13, v13, v13 quad_perm:[1,0,3,2] row_mask:0xf bank_mask:0xf bound_ctrl:1
	v_pk_fma_f32 v[18:19], v[2:3], v[86:87], v[18:19]
	v_add_f32_dpp v12, v12, v12 quad_perm:[2,3,0,1] row_mask:0xf bank_mask:0xf bound_ctrl:1
	v_add_f32_dpp v13, v13, v13 quad_perm:[2,3,0,1] row_mask:0xf bank_mask:0xf bound_ctrl:1
	v_pk_fma_f32 v[20:21], v[4:5], v[88:89], v[20:21]
	v_add_f32_dpp v12, v12, v12 row_half_mirror row_mask:0xf bank_mask:0xf bound_ctrl:1
	v_add_f32_dpp v13, v13, v13 row_half_mirror row_mask:0xf bank_mask:0xf bound_ctrl:1
	s_nop 0
	v_add_f32_dpp v12, v12, v12 row_mirror row_mask:0xf bank_mask:0xf bound_ctrl:1
	v_add_f32_dpp v13, v13, v13 row_mirror row_mask:0xf bank_mask:0xf bound_ctrl:1
	v_pk_fma_f32 v[2:3], v[90:91], v[12:13], v[18:19] op_sel_hi:[1,0,1]
	v_pk_fma_f32 v[4:5], v[92:93], v[12:13], v[20:21] op_sel_hi:[1,0,1]
	v_fmac_f32_e32 v13, v122, v12
	v_fmac_f32_e32 v13, v119, v123
	ds_write2_b32 v22, v11, v13 offset0:64 offset1:80
	s_waitcnt lgkmcnt(11)
	ds_read_b64 v[58:59], v6 offset:30720
	ds_read_b64 v[60:61], v6 offset:30728
	ds_read_b64 v[62:63], v6 offset:30736
	ds_read_b64 v[64:65], v6 offset:30744
	ds_read_b64 v[66:67], v6 offset:30752
	ds_read_b64 v[68:69], v6 offset:30760
	ds_read_b64 v[70:71], v6 offset:30768
	ds_read_b64 v[72:73], v6 offset:30776
	ds_read_b64 v[74:75], v6 offset:30784
	ds_read_b64 v[76:77], v6 offset:30792
	ds_read2st64_b32 v[118:119], v7 offset0:24 offset1:25
	ds_read_b128 v[120:123], v8 offset:192
	v_pk_mul_f32 v[14:15], v[2:3], v[98:99] op_sel_hi:[0,1]
	v_pk_fma_f32 v[14:15], v[2:3], v[100:101], v[14:15] op_sel:[1,0,0] op_sel_hi:[1,1,1]
	v_pk_fma_f32 v[14:15], v[4:5], v[102:103], v[14:15] op_sel_hi:[0,1,1]
	v_pk_fma_f32 v[14:15], v[4:5], v[104:105], v[14:15] op_sel:[1,0,0] op_sel_hi:[1,1,1]
	v_pk_mul_f32 v[18:19], v[114:115], v[206:207] op_sel_hi:[1,0]
	v_pk_mul_f32 v[20:21], v[116:117], v[206:207] op_sel_hi:[1,0]
	v_add_f32_dpp v14, v14, v14 quad_perm:[1,0,3,2] row_mask:0xf bank_mask:0xf bound_ctrl:1
	v_add_f32_dpp v15, v15, v15 quad_perm:[1,0,3,2] row_mask:0xf bank_mask:0xf bound_ctrl:1
	v_pk_fma_f32 v[18:19], v[2:3], v[106:107], v[18:19]
	v_add_f32_dpp v14, v14, v14 quad_perm:[2,3,0,1] row_mask:0xf bank_mask:0xf bound_ctrl:1
	v_add_f32_dpp v15, v15, v15 quad_perm:[2,3,0,1] row_mask:0xf bank_mask:0xf bound_ctrl:1
	v_pk_fma_f32 v[20:21], v[4:5], v[108:109], v[20:21]
	v_add_f32_dpp v14, v14, v14 row_half_mirror row_mask:0xf bank_mask:0xf bound_ctrl:1
	v_add_f32_dpp v15, v15, v15 row_half_mirror row_mask:0xf bank_mask:0xf bound_ctrl:1
	s_nop 0
	v_add_f32_dpp v14, v14, v14 row_mirror row_mask:0xf bank_mask:0xf bound_ctrl:1
	v_add_f32_dpp v15, v15, v15 row_mirror row_mask:0xf bank_mask:0xf bound_ctrl:1
	v_pk_fma_f32 v[2:3], v[110:111], v[14:15], v[18:19] op_sel_hi:[1,0,1]
	v_pk_fma_f32 v[4:5], v[112:113], v[14:15], v[20:21] op_sel_hi:[1,0,1]
	v_fmac_f32_e32 v15, v208, v14
	v_fmac_f32_e32 v15, v206, v209
	s_waitcnt lgkmcnt(13)
	ds_read_b64 v[78:79], v6 offset:32000
	ds_read_b64 v[80:81], v6 offset:32008
	ds_read_b64 v[82:83], v6 offset:32016
	ds_read_b64 v[84:85], v6 offset:32024
	ds_read_b64 v[86:87], v6 offset:32032
	ds_read_b64 v[88:89], v6 offset:32040
	ds_read_b64 v[90:91], v6 offset:32048
	ds_read_b64 v[92:93], v6 offset:32056
	ds_read_b64 v[94:95], v6 offset:32064
	ds_read_b64 v[96:97], v6 offset:32072
	v_pk_mul_f32 v[16:17], v[2:3], v[186:187] op_sel_hi:[0,1]
	v_pk_fma_f32 v[16:17], v[2:3], v[188:189], v[16:17] op_sel:[1,0,0] op_sel_hi:[1,1,1]
	v_pk_fma_f32 v[16:17], v[4:5], v[190:191], v[16:17] op_sel_hi:[0,1,1]
	v_pk_fma_f32 v[16:17], v[4:5], v[192:193], v[16:17] op_sel:[1,0,0] op_sel_hi:[1,1,1]
	v_pk_mul_f32 v[18:19], v[202:203], v[206:207] op_sel:[0,1] op_sel_hi:[1,1]
	v_pk_mul_f32 v[20:21], v[204:205], v[206:207] op_sel:[0,1] op_sel_hi:[1,1]
	v_add_f32_dpp v16, v16, v16 quad_perm:[1,0,3,2] row_mask:0xf bank_mask:0xf bound_ctrl:1
	v_add_f32_dpp v17, v17, v17 quad_perm:[1,0,3,2] row_mask:0xf bank_mask:0xf bound_ctrl:1
	v_pk_fma_f32 v[18:19], v[2:3], v[194:195], v[18:19]
	v_add_f32_dpp v16, v16, v16 quad_perm:[2,3,0,1] row_mask:0xf bank_mask:0xf bound_ctrl:1
	v_add_f32_dpp v17, v17, v17 quad_perm:[2,3,0,1] row_mask:0xf bank_mask:0xf bound_ctrl:1
	v_pk_fma_f32 v[20:21], v[4:5], v[196:197], v[20:21]
	v_add_f32_dpp v16, v16, v16 row_half_mirror row_mask:0xf bank_mask:0xf bound_ctrl:1
	v_add_f32_dpp v17, v17, v17 row_half_mirror row_mask:0xf bank_mask:0xf bound_ctrl:1
	s_nop 0
	v_add_f32_dpp v16, v16, v16 row_mirror row_mask:0xf bank_mask:0xf bound_ctrl:1
	v_add_f32_dpp v17, v17, v17 row_mirror row_mask:0xf bank_mask:0xf bound_ctrl:1
	v_pk_fma_f32 v[2:3], v[198:199], v[16:17], v[18:19] op_sel_hi:[1,0,1]
	v_pk_fma_f32 v[4:5], v[200:201], v[16:17], v[20:21] op_sel_hi:[1,0,1]
	v_fmac_f32_e32 v17, v210, v16
	v_fmac_f32_e32 v17, v207, v211
	ds_write2_b32 v22, v15, v17 offset0:96 offset1:112
	s_waitcnt lgkmcnt(11)
	ds_read_b64 v[98:99], v6 offset:33280
	ds_read_b64 v[100:101], v6 offset:33288
	ds_read_b64 v[102:103], v6 offset:33296
	ds_read_b64 v[104:105], v6 offset:33304
	ds_read_b64 v[106:107], v6 offset:33312
	ds_read_b64 v[108:109], v6 offset:33320
	ds_read_b64 v[110:111], v6 offset:33328
	ds_read_b64 v[112:113], v6 offset:33336
	ds_read_b64 v[114:115], v6 offset:33344
	ds_read_b64 v[116:117], v6 offset:33352
	ds_read2st64_b32 v[206:207], v7 offset0:26 offset1:27
	ds_read_b128 v[208:211], v8 offset:208
	v_pk_mul_f32 v[10:11], v[2:3], v[58:59] op_sel_hi:[0,1]
	v_pk_fma_f32 v[10:11], v[2:3], v[60:61], v[10:11] op_sel:[1,0,0] op_sel_hi:[1,1,1]
	v_pk_fma_f32 v[10:11], v[4:5], v[62:63], v[10:11] op_sel_hi:[0,1,1]
	v_pk_fma_f32 v[10:11], v[4:5], v[64:65], v[10:11] op_sel:[1,0,0] op_sel_hi:[1,1,1]
	v_pk_mul_f32 v[18:19], v[74:75], v[118:119] op_sel_hi:[1,0]
	v_pk_mul_f32 v[20:21], v[76:77], v[118:119] op_sel_hi:[1,0]
	v_add_f32_dpp v10, v10, v10 quad_perm:[1,0,3,2] row_mask:0xf bank_mask:0xf bound_ctrl:1
	v_add_f32_dpp v11, v11, v11 quad_perm:[1,0,3,2] row_mask:0xf bank_mask:0xf bound_ctrl:1
	v_pk_fma_f32 v[18:19], v[2:3], v[66:67], v[18:19]
	v_add_f32_dpp v10, v10, v10 quad_perm:[2,3,0,1] row_mask:0xf bank_mask:0xf bound_ctrl:1
	v_add_f32_dpp v11, v11, v11 quad_perm:[2,3,0,1] row_mask:0xf bank_mask:0xf bound_ctrl:1
	v_pk_fma_f32 v[20:21], v[4:5], v[68:69], v[20:21]
	v_add_f32_dpp v10, v10, v10 row_half_mirror row_mask:0xf bank_mask:0xf bound_ctrl:1
	v_add_f32_dpp v11, v11, v11 row_half_mirror row_mask:0xf bank_mask:0xf bound_ctrl:1
	s_nop 0
	v_add_f32_dpp v10, v10, v10 row_mirror row_mask:0xf bank_mask:0xf bound_ctrl:1
	v_add_f32_dpp v11, v11, v11 row_mirror row_mask:0xf bank_mask:0xf bound_ctrl:1
	v_pk_fma_f32 v[2:3], v[70:71], v[10:11], v[18:19] op_sel_hi:[1,0,1]
	v_pk_fma_f32 v[4:5], v[72:73], v[10:11], v[20:21] op_sel_hi:[1,0,1]
	v_fmac_f32_e32 v11, v120, v10
	v_fmac_f32_e32 v11, v118, v121
	s_waitcnt lgkmcnt(13)
	ds_read_b64 v[186:187], v6 offset:34560
	ds_read_b64 v[188:189], v6 offset:34568
	ds_read_b64 v[190:191], v6 offset:34576
	ds_read_b64 v[192:193], v6 offset:34584
	ds_read_b64 v[194:195], v6 offset:34592
	ds_read_b64 v[196:197], v6 offset:34600
	ds_read_b64 v[198:199], v6 offset:34608
	ds_read_b64 v[200:201], v6 offset:34616
	ds_read_b64 v[202:203], v6 offset:34624
	ds_read_b64 v[204:205], v6 offset:34632
	v_pk_mul_f32 v[12:13], v[2:3], v[78:79] op_sel_hi:[0,1]
	v_pk_fma_f32 v[12:13], v[2:3], v[80:81], v[12:13] op_sel:[1,0,0] op_sel_hi:[1,1,1]
	v_pk_fma_f32 v[12:13], v[4:5], v[82:83], v[12:13] op_sel_hi:[0,1,1]
	v_pk_fma_f32 v[12:13], v[4:5], v[84:85], v[12:13] op_sel:[1,0,0] op_sel_hi:[1,1,1]
	v_pk_mul_f32 v[18:19], v[94:95], v[118:119] op_sel:[0,1] op_sel_hi:[1,1]
	v_pk_mul_f32 v[20:21], v[96:97], v[118:119] op_sel:[0,1] op_sel_hi:[1,1]
	v_add_f32_dpp v12, v12, v12 quad_perm:[1,0,3,2] row_mask:0xf bank_mask:0xf bound_ctrl:1
	v_add_f32_dpp v13, v13, v13 quad_perm:[1,0,3,2] row_mask:0xf bank_mask:0xf bound_ctrl:1
	v_pk_fma_f32 v[18:19], v[2:3], v[86:87], v[18:19]
	v_add_f32_dpp v12, v12, v12 quad_perm:[2,3,0,1] row_mask:0xf bank_mask:0xf bound_ctrl:1
	v_add_f32_dpp v13, v13, v13 quad_perm:[2,3,0,1] row_mask:0xf bank_mask:0xf bound_ctrl:1
	v_pk_fma_f32 v[20:21], v[4:5], v[88:89], v[20:21]
	v_add_f32_dpp v12, v12, v12 row_half_mirror row_mask:0xf bank_mask:0xf bound_ctrl:1
	v_add_f32_dpp v13, v13, v13 row_half_mirror row_mask:0xf bank_mask:0xf bound_ctrl:1
	s_nop 0
	v_add_f32_dpp v12, v12, v12 row_mirror row_mask:0xf bank_mask:0xf bound_ctrl:1
	v_add_f32_dpp v13, v13, v13 row_mirror row_mask:0xf bank_mask:0xf bound_ctrl:1
	v_pk_fma_f32 v[2:3], v[90:91], v[12:13], v[18:19] op_sel_hi:[1,0,1]
	v_pk_fma_f32 v[4:5], v[92:93], v[12:13], v[20:21] op_sel_hi:[1,0,1]
	v_fmac_f32_e32 v13, v122, v12
	v_fmac_f32_e32 v13, v119, v123
	ds_write2_b32 v22, v11, v13 offset0:128 offset1:144
	s_waitcnt lgkmcnt(11)
	ds_read_b64 v[58:59], v6 offset:35840
	ds_read_b64 v[60:61], v6 offset:35848
	ds_read_b64 v[62:63], v6 offset:35856
	ds_read_b64 v[64:65], v6 offset:35864
	ds_read_b64 v[66:67], v6 offset:35872
	ds_read_b64 v[68:69], v6 offset:35880
	ds_read_b64 v[70:71], v6 offset:35888
	ds_read_b64 v[72:73], v6 offset:35896
	ds_read_b64 v[74:75], v6 offset:35904
	ds_read_b64 v[76:77], v6 offset:35912
	ds_read2st64_b32 v[118:119], v7 offset0:28 offset1:29
	ds_read_b128 v[120:123], v8 offset:224
	v_pk_mul_f32 v[14:15], v[2:3], v[98:99] op_sel_hi:[0,1]
	v_pk_fma_f32 v[14:15], v[2:3], v[100:101], v[14:15] op_sel:[1,0,0] op_sel_hi:[1,1,1]
	v_pk_fma_f32 v[14:15], v[4:5], v[102:103], v[14:15] op_sel_hi:[0,1,1]
	v_pk_fma_f32 v[14:15], v[4:5], v[104:105], v[14:15] op_sel:[1,0,0] op_sel_hi:[1,1,1]
	v_pk_mul_f32 v[18:19], v[114:115], v[206:207] op_sel_hi:[1,0]
	v_pk_mul_f32 v[20:21], v[116:117], v[206:207] op_sel_hi:[1,0]
	v_add_f32_dpp v14, v14, v14 quad_perm:[1,0,3,2] row_mask:0xf bank_mask:0xf bound_ctrl:1
	v_add_f32_dpp v15, v15, v15 quad_perm:[1,0,3,2] row_mask:0xf bank_mask:0xf bound_ctrl:1
	v_pk_fma_f32 v[18:19], v[2:3], v[106:107], v[18:19]
	v_add_f32_dpp v14, v14, v14 quad_perm:[2,3,0,1] row_mask:0xf bank_mask:0xf bound_ctrl:1
	v_add_f32_dpp v15, v15, v15 quad_perm:[2,3,0,1] row_mask:0xf bank_mask:0xf bound_ctrl:1
	v_pk_fma_f32 v[20:21], v[4:5], v[108:109], v[20:21]
	v_add_f32_dpp v14, v14, v14 row_half_mirror row_mask:0xf bank_mask:0xf bound_ctrl:1
	v_add_f32_dpp v15, v15, v15 row_half_mirror row_mask:0xf bank_mask:0xf bound_ctrl:1
	s_nop 0
	v_add_f32_dpp v14, v14, v14 row_mirror row_mask:0xf bank_mask:0xf bound_ctrl:1
	v_add_f32_dpp v15, v15, v15 row_mirror row_mask:0xf bank_mask:0xf bound_ctrl:1
	v_pk_fma_f32 v[2:3], v[110:111], v[14:15], v[18:19] op_sel_hi:[1,0,1]
	v_pk_fma_f32 v[4:5], v[112:113], v[14:15], v[20:21] op_sel_hi:[1,0,1]
	v_fmac_f32_e32 v15, v208, v14
	v_fmac_f32_e32 v15, v206, v209
	s_waitcnt lgkmcnt(13)
	ds_read_b64 v[78:79], v6 offset:37120
	ds_read_b64 v[80:81], v6 offset:37128
	ds_read_b64 v[82:83], v6 offset:37136
	ds_read_b64 v[84:85], v6 offset:37144
	ds_read_b64 v[86:87], v6 offset:37152
	ds_read_b64 v[88:89], v6 offset:37160
	ds_read_b64 v[90:91], v6 offset:37168
	ds_read_b64 v[92:93], v6 offset:37176
	ds_read_b64 v[94:95], v6 offset:37184
	ds_read_b64 v[96:97], v6 offset:37192
	v_pk_mul_f32 v[16:17], v[2:3], v[186:187] op_sel_hi:[0,1]
	v_pk_fma_f32 v[16:17], v[2:3], v[188:189], v[16:17] op_sel:[1,0,0] op_sel_hi:[1,1,1]
	v_pk_fma_f32 v[16:17], v[4:5], v[190:191], v[16:17] op_sel_hi:[0,1,1]
	v_pk_fma_f32 v[16:17], v[4:5], v[192:193], v[16:17] op_sel:[1,0,0] op_sel_hi:[1,1,1]
	v_pk_mul_f32 v[18:19], v[202:203], v[206:207] op_sel:[0,1] op_sel_hi:[1,1]
	v_pk_mul_f32 v[20:21], v[204:205], v[206:207] op_sel:[0,1] op_sel_hi:[1,1]
	v_add_f32_dpp v16, v16, v16 quad_perm:[1,0,3,2] row_mask:0xf bank_mask:0xf bound_ctrl:1
	v_add_f32_dpp v17, v17, v17 quad_perm:[1,0,3,2] row_mask:0xf bank_mask:0xf bound_ctrl:1
	v_pk_fma_f32 v[18:19], v[2:3], v[194:195], v[18:19]
	v_add_f32_dpp v16, v16, v16 quad_perm:[2,3,0,1] row_mask:0xf bank_mask:0xf bound_ctrl:1
	v_add_f32_dpp v17, v17, v17 quad_perm:[2,3,0,1] row_mask:0xf bank_mask:0xf bound_ctrl:1
	v_pk_fma_f32 v[20:21], v[4:5], v[196:197], v[20:21]
	v_add_f32_dpp v16, v16, v16 row_half_mirror row_mask:0xf bank_mask:0xf bound_ctrl:1
	v_add_f32_dpp v17, v17, v17 row_half_mirror row_mask:0xf bank_mask:0xf bound_ctrl:1
	s_nop 0
	v_add_f32_dpp v16, v16, v16 row_mirror row_mask:0xf bank_mask:0xf bound_ctrl:1
	v_add_f32_dpp v17, v17, v17 row_mirror row_mask:0xf bank_mask:0xf bound_ctrl:1
	v_pk_fma_f32 v[2:3], v[198:199], v[16:17], v[18:19] op_sel_hi:[1,0,1]
	v_pk_fma_f32 v[4:5], v[200:201], v[16:17], v[20:21] op_sel_hi:[1,0,1]
	v_fmac_f32_e32 v17, v210, v16
	v_fmac_f32_e32 v17, v207, v211
	ds_write2_b32 v22, v15, v17 offset0:160 offset1:176
	s_waitcnt lgkmcnt(11)
	ds_read_b64 v[98:99], v6 offset:38400
	ds_read_b64 v[100:101], v6 offset:38408
	ds_read_b64 v[102:103], v6 offset:38416
	ds_read_b64 v[104:105], v6 offset:38424
	ds_read_b64 v[106:107], v6 offset:38432
	ds_read_b64 v[108:109], v6 offset:38440
	ds_read_b64 v[110:111], v6 offset:38448
	ds_read_b64 v[112:113], v6 offset:38456
	ds_read_b64 v[114:115], v6 offset:38464
	ds_read_b64 v[116:117], v6 offset:38472
	ds_read2st64_b32 v[206:207], v7 offset0:30 offset1:31
	ds_read_b128 v[208:211], v8 offset:240
	v_pk_mul_f32 v[10:11], v[2:3], v[58:59] op_sel_hi:[0,1]
	v_pk_fma_f32 v[10:11], v[2:3], v[60:61], v[10:11] op_sel:[1,0,0] op_sel_hi:[1,1,1]
	v_pk_fma_f32 v[10:11], v[4:5], v[62:63], v[10:11] op_sel_hi:[0,1,1]
	v_pk_fma_f32 v[10:11], v[4:5], v[64:65], v[10:11] op_sel:[1,0,0] op_sel_hi:[1,1,1]
	v_pk_mul_f32 v[18:19], v[74:75], v[118:119] op_sel_hi:[1,0]
	v_pk_mul_f32 v[20:21], v[76:77], v[118:119] op_sel_hi:[1,0]
	v_add_f32_dpp v10, v10, v10 quad_perm:[1,0,3,2] row_mask:0xf bank_mask:0xf bound_ctrl:1
	v_add_f32_dpp v11, v11, v11 quad_perm:[1,0,3,2] row_mask:0xf bank_mask:0xf bound_ctrl:1
	v_pk_fma_f32 v[18:19], v[2:3], v[66:67], v[18:19]
	v_add_f32_dpp v10, v10, v10 quad_perm:[2,3,0,1] row_mask:0xf bank_mask:0xf bound_ctrl:1
	v_add_f32_dpp v11, v11, v11 quad_perm:[2,3,0,1] row_mask:0xf bank_mask:0xf bound_ctrl:1
	v_pk_fma_f32 v[20:21], v[4:5], v[68:69], v[20:21]
	v_add_f32_dpp v10, v10, v10 row_half_mirror row_mask:0xf bank_mask:0xf bound_ctrl:1
	v_add_f32_dpp v11, v11, v11 row_half_mirror row_mask:0xf bank_mask:0xf bound_ctrl:1
	s_nop 0
	v_add_f32_dpp v10, v10, v10 row_mirror row_mask:0xf bank_mask:0xf bound_ctrl:1
	v_add_f32_dpp v11, v11, v11 row_mirror row_mask:0xf bank_mask:0xf bound_ctrl:1
	v_pk_fma_f32 v[2:3], v[70:71], v[10:11], v[18:19] op_sel_hi:[1,0,1]
	v_pk_fma_f32 v[4:5], v[72:73], v[10:11], v[20:21] op_sel_hi:[1,0,1]
	v_fmac_f32_e32 v11, v120, v10
	v_fmac_f32_e32 v11, v118, v121
	s_waitcnt lgkmcnt(13)
	ds_read_b64 v[186:187], v6 offset:39680
	ds_read_b64 v[188:189], v6 offset:39688
	ds_read_b64 v[190:191], v6 offset:39696
	ds_read_b64 v[192:193], v6 offset:39704
	ds_read_b64 v[194:195], v6 offset:39712
	ds_read_b64 v[196:197], v6 offset:39720
	ds_read_b64 v[198:199], v6 offset:39728
	ds_read_b64 v[200:201], v6 offset:39736
	ds_read_b64 v[202:203], v6 offset:39744
	ds_read_b64 v[204:205], v6 offset:39752
	v_pk_mul_f32 v[12:13], v[2:3], v[78:79] op_sel_hi:[0,1]
	v_pk_fma_f32 v[12:13], v[2:3], v[80:81], v[12:13] op_sel:[1,0,0] op_sel_hi:[1,1,1]
	v_pk_fma_f32 v[12:13], v[4:5], v[82:83], v[12:13] op_sel_hi:[0,1,1]
	v_pk_fma_f32 v[12:13], v[4:5], v[84:85], v[12:13] op_sel:[1,0,0] op_sel_hi:[1,1,1]
	v_pk_mul_f32 v[18:19], v[94:95], v[118:119] op_sel:[0,1] op_sel_hi:[1,1]
	v_pk_mul_f32 v[20:21], v[96:97], v[118:119] op_sel:[0,1] op_sel_hi:[1,1]
	v_add_f32_dpp v12, v12, v12 quad_perm:[1,0,3,2] row_mask:0xf bank_mask:0xf bound_ctrl:1
	v_add_f32_dpp v13, v13, v13 quad_perm:[1,0,3,2] row_mask:0xf bank_mask:0xf bound_ctrl:1
	v_pk_fma_f32 v[18:19], v[2:3], v[86:87], v[18:19]
	v_add_f32_dpp v12, v12, v12 quad_perm:[2,3,0,1] row_mask:0xf bank_mask:0xf bound_ctrl:1
	v_add_f32_dpp v13, v13, v13 quad_perm:[2,3,0,1] row_mask:0xf bank_mask:0xf bound_ctrl:1
	v_pk_fma_f32 v[20:21], v[4:5], v[88:89], v[20:21]
	v_add_f32_dpp v12, v12, v12 row_half_mirror row_mask:0xf bank_mask:0xf bound_ctrl:1
	v_add_f32_dpp v13, v13, v13 row_half_mirror row_mask:0xf bank_mask:0xf bound_ctrl:1
	s_nop 0
	v_add_f32_dpp v12, v12, v12 row_mirror row_mask:0xf bank_mask:0xf bound_ctrl:1
	v_add_f32_dpp v13, v13, v13 row_mirror row_mask:0xf bank_mask:0xf bound_ctrl:1
	v_pk_fma_f32 v[2:3], v[90:91], v[12:13], v[18:19] op_sel_hi:[1,0,1]
	v_pk_fma_f32 v[4:5], v[92:93], v[12:13], v[20:21] op_sel_hi:[1,0,1]
	v_fmac_f32_e32 v13, v122, v12
	v_fmac_f32_e32 v13, v119, v123
	ds_write2_b32 v22, v11, v13 offset0:192 offset1:208
	s_waitcnt lgkmcnt(11)
	v_pk_mul_f32 v[14:15], v[2:3], v[98:99] op_sel_hi:[0,1]
	v_pk_fma_f32 v[14:15], v[2:3], v[100:101], v[14:15] op_sel:[1,0,0] op_sel_hi:[1,1,1]
	v_pk_fma_f32 v[14:15], v[4:5], v[102:103], v[14:15] op_sel_hi:[0,1,1]
	v_pk_fma_f32 v[14:15], v[4:5], v[104:105], v[14:15] op_sel:[1,0,0] op_sel_hi:[1,1,1]
	v_pk_mul_f32 v[18:19], v[114:115], v[206:207] op_sel_hi:[1,0]
	v_pk_mul_f32 v[20:21], v[116:117], v[206:207] op_sel_hi:[1,0]
	v_add_f32_dpp v14, v14, v14 quad_perm:[1,0,3,2] row_mask:0xf bank_mask:0xf bound_ctrl:1
	v_add_f32_dpp v15, v15, v15 quad_perm:[1,0,3,2] row_mask:0xf bank_mask:0xf bound_ctrl:1
	v_pk_fma_f32 v[18:19], v[2:3], v[106:107], v[18:19]
	v_add_f32_dpp v14, v14, v14 quad_perm:[2,3,0,1] row_mask:0xf bank_mask:0xf bound_ctrl:1
	v_add_f32_dpp v15, v15, v15 quad_perm:[2,3,0,1] row_mask:0xf bank_mask:0xf bound_ctrl:1
	v_pk_fma_f32 v[20:21], v[4:5], v[108:109], v[20:21]
	v_add_f32_dpp v14, v14, v14 row_half_mirror row_mask:0xf bank_mask:0xf bound_ctrl:1
	v_add_f32_dpp v15, v15, v15 row_half_mirror row_mask:0xf bank_mask:0xf bound_ctrl:1
	s_nop 0
	v_add_f32_dpp v14, v14, v14 row_mirror row_mask:0xf bank_mask:0xf bound_ctrl:1
	v_add_f32_dpp v15, v15, v15 row_mirror row_mask:0xf bank_mask:0xf bound_ctrl:1
	v_pk_fma_f32 v[2:3], v[110:111], v[14:15], v[18:19] op_sel_hi:[1,0,1]
	v_pk_fma_f32 v[4:5], v[112:113], v[14:15], v[20:21] op_sel_hi:[1,0,1]
	v_fmac_f32_e32 v15, v208, v14
	v_fmac_f32_e32 v15, v206, v209
	s_waitcnt lgkmcnt(1)
	v_pk_mul_f32 v[16:17], v[2:3], v[186:187] op_sel_hi:[0,1]
	v_pk_fma_f32 v[16:17], v[2:3], v[188:189], v[16:17] op_sel:[1,0,0] op_sel_hi:[1,1,1]
	v_pk_fma_f32 v[16:17], v[4:5], v[190:191], v[16:17] op_sel_hi:[0,1,1]
	v_pk_fma_f32 v[16:17], v[4:5], v[192:193], v[16:17] op_sel:[1,0,0] op_sel_hi:[1,1,1]
	v_pk_mul_f32 v[18:19], v[202:203], v[206:207] op_sel:[0,1] op_sel_hi:[1,1]
	v_pk_mul_f32 v[20:21], v[204:205], v[206:207] op_sel:[0,1] op_sel_hi:[1,1]
	v_add_f32_dpp v16, v16, v16 quad_perm:[1,0,3,2] row_mask:0xf bank_mask:0xf bound_ctrl:1
	v_add_f32_dpp v17, v17, v17 quad_perm:[1,0,3,2] row_mask:0xf bank_mask:0xf bound_ctrl:1
	v_pk_fma_f32 v[18:19], v[2:3], v[194:195], v[18:19]
	v_add_f32_dpp v16, v16, v16 quad_perm:[2,3,0,1] row_mask:0xf bank_mask:0xf bound_ctrl:1
	v_add_f32_dpp v17, v17, v17 quad_perm:[2,3,0,1] row_mask:0xf bank_mask:0xf bound_ctrl:1
	v_pk_fma_f32 v[20:21], v[4:5], v[196:197], v[20:21]
	v_add_f32_dpp v16, v16, v16 row_half_mirror row_mask:0xf bank_mask:0xf bound_ctrl:1
	v_add_f32_dpp v17, v17, v17 row_half_mirror row_mask:0xf bank_mask:0xf bound_ctrl:1
	s_nop 0
	v_add_f32_dpp v16, v16, v16 row_mirror row_mask:0xf bank_mask:0xf bound_ctrl:1
	v_add_f32_dpp v17, v17, v17 row_mirror row_mask:0xf bank_mask:0xf bound_ctrl:1
	v_pk_fma_f32 v[2:3], v[198:199], v[16:17], v[18:19] op_sel_hi:[1,0,1]
	v_pk_fma_f32 v[4:5], v[200:201], v[16:17], v[20:21] op_sel_hi:[1,0,1]
	v_fmac_f32_e32 v17, v210, v16
	v_fmac_f32_e32 v17, v207, v211
	ds_write2_b32 v22, v15, v17 offset0:224 offset1:240
	s_add_i32 s0, s0, 1
	s_cmpk_lg_i32 s0, 0x80
	s_waitcnt lgkmcnt(0)
	s_barrier
	s_cbranch_scc1 .LBB0_726
